# INPROJ converted too: 128x256 tiles, LDS-DMA staging, K-blocked w_in; K-loops rolled into 3-stage loops
# speedup vs baseline: 1.0915x; 1.0429x over previous
; DI void st8(u16* dst, const float (&v)[8]) { *(u32x4*)dst = pack8(v); }
; DI int colmap(int mode, int n) {
;   if (mode == 1) return n < 5248 ? n : (n < 5280 ? 8832 + (n - 5248) : n - 32);
;   if (mode == 2) return (n / 96) * 128 + (n % 96);
;   return n;
; }
; DI void prep_tile(const float* __restrict__ W, int K, int N, const float* __restrict__ gain, u16* __restrict__ dst, int mode, int tile, char* smem) {
;     ...
;   for (int i = 0; i < 2; ++i) {
;     const int cid = tid + 256 * i, nl = cid >> 3, kc = cid & 7, n = n0 + nl;
;     if (n < N) {
;       float v[8];
; #pragma unroll
;       for (int j = 0; j < 8; ++j) v[j] = Ts[nl * 65 + kc * 8 + j];
;       st8(dst + (size_t)colmap(mode, n) * K + k0 + kc * 8, v);
;     }
;   }
.LBB1_41:
	s_mov_b32 s40, 0
	s_cmp_eq_u32 s73, 8
	s_cselect_b32 s40, 0x40000, s40
	s_cmp_eq_u32 s73, 9
	s_cselect_b32 s40, 0x10000, s40
	s_cmp_eq_u32 s73, 18
	s_cselect_b32 s40, 0x40000, s40
	s_cmp_eq_u32 s73, 19
	s_cselect_b32 s40, 0x10000, s40
	s_cmp_eq_u32 s73, 0
	s_cbranch_scc1 .Lprep_win2
	s_cmp_eq_u32 s73, 10
	s_cbranch_scc1 .Lprep_win2
	s_cmp_eq_u32 s40, 0
	s_cbranch_scc0 .Lprep_blk2
	v_ashrrev_i32_e32 v16, 31, v14
	v_mad_u64_u32 v[14:15], s[40:41], v14, s74, 0
	v_mov_b32_e32 v2, v15
	v_mad_u64_u32 v[16:17], s[40:41], v16, s74, v[2:3]
	v_mov_b32_e32 v15, v16
	v_lshl_add_u64 v[14:15], v[14:15], 1, v[4:5]
	s_branch .Lprep_st2
.Lprep_blk2:
	v_subrev_u32_e32 v15, s34, v4
	v_lshrrev_b32_e32 v16, 6, v15
	v_and_b32_e32 v15, 63, v15
	v_mul_lo_u32 v16, v16, s40
	v_lshl_add_u32 v14, v14, 6, v15
	v_add_u32_e32 v14, v14, v16
	v_mov_b32_e32 v15, 0
	v_lshl_add_u64 v[14:15], s[34:35], 0, v[14:15]
	s_branch .Lprep_st2
.Lprep_win2:
	v_mov_b32_e32 v42, v14
	v_ashrrev_i32_e32 v16, 31, v14
	v_mad_u64_u32 v[14:15], s[40:41], v14, s74, 0
	v_mov_b32_e32 v2, v15
	v_mad_u64_u32 v[16:17], s[40:41], v16, s74, v[2:3]
	v_mov_b32_e32 v15, v16
	v_lshl_add_u64 v[14:15], v[14:15], 1, v[4:5]
	v_subrev_u32_e32 v43, s34, v4
	v_lshrrev_b32_e32 v44, 6, v43
	v_and_b32_e32 v43, 63, v43
	v_lshl_add_u32 v45, v42, 6, v43
	s_mov_b32 s40, 0x5a000
	v_mul_lo_u32 v46, v44, s40
	v_add_u32_e32 v46, v46, v45
	v_lshl_add_u32 v47, v44, 13, v45
	v_add_u32_e32 v47, 0x10b6000, v47
	v_cmp_gt_u32_e32 vcc, 0x1680, v42
	s_nop 1
	v_cndmask_b32_e32 v46, v47, v46, vcc
	v_mov_b32_e32 v47, 0
	v_lshl_add_u64 v[46:47], s[34:35], 0, v[46:47]
	v_subrev_u32_e32 v43, 0x1680, v42
	v_cmp_gt_u32_e32 vcc, 0xc00, v43
	s_nop 1
	v_cndmask_b32_e32 v14, v46, v14, vcc
	v_cndmask_b32_e32 v15, v47, v15, vcc
	s_branch .Lprep_st2

; DI void st8(u16* dst, const float (&v)[8]) { *(u32x4*)dst = pack8(v); }
; DI int colmap(int mode, int n) {
;   if (mode == 1) return n < 5248 ? n : (n < 5280 ? 8832 + (n - 5248) : n - 32);
;   if (mode == 2) return (n / 96) * 128 + (n % 96);
;   return n;
; }
; DI void prep_tile(const float* __restrict__ W, int K, int N, const float* __restrict__ gain, u16* __restrict__ dst, int mode, int tile, char* smem) {
;     ...
;   for (int i = 0; i < 2; ++i) {
;     const int cid = tid + 256 * i, nl = cid >> 3, kc = cid & 7, n = n0 + nl;
;     if (n < N) {
;       float v[8];
; #pragma unroll
;       for (int j = 0; j < 8; ++j) v[j] = Ts[nl * 65 + kc * 8 + j];
;       st8(dst + (size_t)colmap(mode, n) * K + k0 + kc * 8, v);
;     }
;   }
.LBB1_122:
	s_mov_b32 s40, 0
	s_cmp_eq_u32 s73, 8
	s_cselect_b32 s40, 0x40000, s40
	s_cmp_eq_u32 s73, 9
	s_cselect_b32 s40, 0x10000, s40
	s_cmp_eq_u32 s73, 18
	s_cselect_b32 s40, 0x40000, s40
	s_cmp_eq_u32 s73, 19
	s_cselect_b32 s40, 0x10000, s40
	s_cmp_eq_u32 s73, 0
	s_cbranch_scc1 .Lprep_win1
	s_cmp_eq_u32 s73, 10
	s_cbranch_scc1 .Lprep_win1
	s_cmp_eq_u32 s40, 0
	s_cbranch_scc0 .Lprep_blk1
	v_ashrrev_i32_e32 v18, 31, v16
	v_mad_u64_u32 v[16:17], s[40:41], v16, s74, 0
	v_mov_b32_e32 v2, v17
	v_mad_u64_u32 v[18:19], s[40:41], v18, s74, v[2:3]
	v_mov_b32_e32 v17, v18
	v_lshl_add_u64 v[16:17], v[16:17], 1, v[4:5]
	s_branch .Lprep_st1
.Lprep_blk1:
	v_subrev_u32_e32 v17, s34, v4
	v_lshrrev_b32_e32 v18, 6, v17
	v_and_b32_e32 v17, 63, v17
	v_mul_lo_u32 v18, v18, s40
	v_lshl_add_u32 v16, v16, 6, v17
	v_add_u32_e32 v16, v16, v18
	v_mov_b32_e32 v17, 0
	v_lshl_add_u64 v[16:17], s[34:35], 0, v[16:17]
	s_branch .Lprep_st1
.Lprep_win1:
	v_mov_b32_e32 v42, v16
	v_ashrrev_i32_e32 v18, 31, v16
	v_mad_u64_u32 v[16:17], s[40:41], v16, s74, 0
	v_mov_b32_e32 v2, v17
	v_mad_u64_u32 v[18:19], s[40:41], v18, s74, v[2:3]
	v_mov_b32_e32 v17, v18
	v_lshl_add_u64 v[16:17], v[16:17], 1, v[4:5]
	v_subrev_u32_e32 v43, s34, v4
	v_lshrrev_b32_e32 v44, 6, v43
	v_and_b32_e32 v43, 63, v43
	v_lshl_add_u32 v45, v42, 6, v43
	s_mov_b32 s40, 0x5a000
	v_mul_lo_u32 v46, v44, s40
	v_add_u32_e32 v46, v46, v45
	v_lshl_add_u32 v47, v44, 13, v45
	v_add_u32_e32 v47, 0x10b6000, v47
	v_cmp_gt_u32_e32 vcc, 0x1680, v42
	s_nop 1
	v_cndmask_b32_e32 v46, v47, v46, vcc
	v_mov_b32_e32 v47, 0
	v_lshl_add_u64 v[46:47], s[34:35], 0, v[46:47]
	v_subrev_u32_e32 v43, 0x1680, v42
	v_cmp_gt_u32_e32 vcc, 0xc00, v43
	s_nop 1
	v_cndmask_b32_e32 v16, v46, v16, vcc
	v_cndmask_b32_e32 v17, v47, v17, vcc
	s_branch .Lprep_st1

; DI int TID() { int t = (int)__builtin_amdgcn_workitem_id_x(); asm volatile("" : "+v"(t)); return t; }
; DI int BID() { int b = (int)__builtin_amdgcn_workgroup_id_x(); asm volatile("" : "+s"(b)); return b; }
; DI void phase_prep(const Params& p, char* smem) {
;     ...
;   const u32x4 z = {0u, 0u, 0u, 0u};
;   const int gtid = BID() * 256 + TID(), gsz = gridDim.x * 256;
;   for (int l = 0; l < 2; ++l) {
;     u16* d1 = (u16*)(p.ws + OFF_WIN + l * SZ_WIN) + (size_t)DIN * 1024;
;     for (int i = gtid; i < 96 * 1024 / 8; i += gsz) *(u32x4*)(d1 + (size_t)i * 8) = z;
;     u16* d2 = (u16*)(p.ws + OFF_WQB + l * SZ_WQB);
;     for (int i = gtid; i < 8 * 32 * 384 / 8; i += gsz) {
;       const int h = i / (32 * 48), rem = i - h * (32 * 48), rr = rem / 48, c8 = rem - rr * 48;
;       *(u32x4*)(d2 + (size_t)(h * 128 + 96 + rr) * 384 + c8 * 8) = z;
;     }
.LBB1_161:
	v_add_u32_e32 v1, s4, v1
	v_cmp_lt_i32_e32 vcc, s5, v1
	s_nop 0
	s_or_b64 s[8:9], vcc, s[8:9]
	v_lshl_add_u64 v[10:11], v[10:11], 0, s[6:7]
	s_andn2_b64 exec, exec, s[8:9]
	s_cbranch_execnz .LBB1_161
	s_or_b64 exec, exec, s[8:9]
	v_mov_b32_e32 v2, 0
	s_mov_b64 s[8:9], 0
	s_mov_b32 s5, 0x2aaaaaab
	s_movk_i32 s10, 0xfa00
	s_movk_i32 s11, 0x60
	s_movk_i32 s12, 0x300
	v_mov_b64_e32 v[10:11], s[24:25]
	v_mov_b32_e32 v3, v2
	v_mov_b32_e32 v4, v2
	v_mov_b32_e32 v5, v2
	s_movk_i32 s13, 0x2fff
	v_mov_b32_e32 v1, v6

; DI int TID() { int t = (int)__builtin_amdgcn_workitem_id_x(); asm volatile("" : "+v"(t)); return t; }
; DI int BID() { int b = (int)__builtin_amdgcn_workgroup_id_x(); asm volatile("" : "+s"(b)); return b; }
; DI void phase_prep(const Params& p, char* smem) {
;     ...
;   const u32x4 z = {0u, 0u, 0u, 0u};
;   const int gtid = BID() * 256 + TID(), gsz = gridDim.x * 256;
;   for (int l = 0; l < 2; ++l) {
;     u16* d1 = (u16*)(p.ws + OFF_WIN + l * SZ_WIN) + (size_t)DIN * 1024;
;     for (int i = gtid; i < 96 * 1024 / 8; i += gsz) *(u32x4*)(d1 + (size_t)i * 8) = z;
;     u16* d2 = (u16*)(p.ws + OFF_WQB + l * SZ_WQB);
;     for (int i = gtid; i < 8 * 32 * 384 / 8; i += gsz) {
;       const int h = i / (32 * 48), rem = i - h * (32 * 48), rr = rem / 48, c8 = rem - rr * 48;
;       *(u32x4*)(d2 + (size_t)(h * 128 + 96 + rr) * 384 + c8 * 8) = z;
;     }
.LBB1_165:
	v_add_u32_e32 v1, s4, v1
	v_cmp_lt_i32_e32 vcc, s5, v1
	s_nop 0
	s_or_b64 s[8:9], vcc, s[8:9]
	v_lshl_add_u64 v[8:9], v[8:9], 0, s[6:7]
	s_andn2_b64 exec, exec, s[8:9]
	s_cbranch_execnz .LBB1_165
	s_or_b64 exec, exec, s[8:9]
	s_add_u32 s12, s76, 0x23c0000
	s_addc_u32 s13, s77, 0
	v_mov_b32_e32 v2, 0
	s_mov_b64 s[6:7], 0
	s_mov_b32 s5, 0x2aaaaaab
	s_movk_i32 s8, 0xfa00
	s_movk_i32 s9, 0x60
	s_movk_i32 s10, 0x300
	v_mov_b64_e32 v[8:9], s[12:13]
	v_mov_b32_e32 v3, v2
	v_mov_b32_e32 v4, v2
	v_mov_b32_e32 v5, v2
	s_movk_i32 s11, 0x2fff

; DI int BID() { int b = (int)__builtin_amdgcn_workgroup_id_x(); asm volatile("" : "+s"(b)); return b; }
; DI void run_phase(const Params& p, int ph, int l, int c, char* smem) {
;     ...
;     default: {
;       PF pf; int t = BID();
;       if (t < MTN * 8) { const u16* A0; const u16* W0; ffn2_ptrs(p, l, t, A0, W0); gemm_issue(pf, A0, 4096, W0, 4096); }
;       for (; t < MTN * 8; t += gridDim.x) { const int tn = t + (int)gridDim.x; tile_ffn2(p, l, ck, t, tn < MTN * 8 ? tn : -1, pf, smem); }
;     } break;
.LBB1_198:
	s_andn2_b64 vcc, exec, s[26:27]
	s_cbranch_vccnz .LBB1_250
	v_readlane_b32 s0, v255, 30
	s_cmp_lg_u32 s0, 8
	s_mov_b64 s[22:23], -1
	s_cbranch_scc0 .LBB1_242
	s_mov_b32 s26, s92
	s_bfe_u32 s0, s26, 0x10008
	s_bfe_u32 s16, s26, 0x20006
	s_andn2_b32 s26, s26, 0x1c0
	s_lshl_b32 s0, s0, 6
	s_lshl_b32 s16, s16, 7
	s_or_b32 s26, s26, s0
	s_or_b32 s26, s26, s16
	s_cmpk_lt_i32 s26, 0x400
	s_cselect_b64 s[22:23], -1, 0
	s_cmpk_gt_i32 s26, 0x3ff
	s_cbranch_scc1 .LBB1_202
	s_lshl_b32 s0, s26, 20
	s_and_b32 s0, s0, 0x7f00000
	s_add_u32 s0, s18, s0
	s_addc_u32 s17, s19, 0
	v_readlane_b32 s24, v255, 28
	s_add_u32 s16, s0, 0x6b80000
	v_readlane_b32 s25, v255, 29
	s_addc_u32 s17, s17, 0
	s_ashr_i32 s25, s24, 31
	s_mov_b32 s0, s24
	v_writelane_b32 v255, s0, 28
	s_lshl_b64 s[24:25], s[24:25], 23
	v_writelane_b32 v255, s1, 29
	s_add_u32 s0, s18, s24
	s_addc_u32 s27, s19, s25
	s_and_b32 s24, s26, 0xffffff80
	s_ashr_i32 s25, s24, 31
	s_lshl_b64 s[24:25], s[24:25], 13
	s_add_u32 s0, s0, s24
	s_addc_u32 s25, s27, s25
	s_add_u32 s24, s0, 0x4380000
	s_movk_i32 s0, 0xe000
	s_addc_u32 s25, s25, 0

; DI int TID() { int t = (int)__builtin_amdgcn_workitem_id_x(); asm volatile("" : "+v"(t)); return t; }
; #define BLOAD(A_, B_, kt) do { _Pragma("unroll") for (int i = 0; i < 4; ++i) { \
;     A_[i] = *(const u32x4*)((const char*)Ap + (aoff + (unsigned)(32 * i * lda + (kt) * 64) * 2u)); B_[i] = *(const u32x4*)((const char*)Wt + (woff + (unsigned)(32 * i * K + (kt) * 64) * 2u)); } } while (0)
; #define BLOAD(A_, B_, kt) do { _Pragma("unroll") for (int i = 0; i < 4; ++i) { \
;     A_[i] = *(const u32x4*)((const char*)Ap + (aoff + (unsigned)(32 * i * lda + (kt) * 64) * 2u)); B_[i] = *(const u32x4*)((const char*)Wt + (woff + (unsigned)(32 * i * K + (kt) * 64) * 2u)); } } while (0)
; #define BSTORE(A_, B_, buf) do { _Pragma("unroll") for (int i = 0; i < 4; ++i) { \
;     *(u32x4*)&As[(buf) * GBUF + (srow + 32 * i) * LDT + sc8] = A_[i]; \
;     *(u32x4*)&Bs[(buf) * GBUF + (srow + 32 * i) * LDT + sc8] = B_[i]; } } while (0)
; template <int NK>
; DI void gemm_run(PF& pf, const u16* __restrict__ Ap, int lda, const u16* __restrict__ Wt, f32x16 (&acc)[2][2], char* smem) {
;     ...
;   __builtin_amdgcn_s_setprio(0);
;   __syncthreads();
;   BSTORE(pf.a0, pf.b0, 0);
;   BLOAD(pf.a0, pf.b0, 2);
;   __syncthreads();
; #pragma unroll
;   for (int kt = 0; kt < nk; kt += 2) {
;     BCOMP(0);
;     BSTORE(pf.a1, pf.b1, 1);
;     if (kt + 3 < nk) BLOAD(pf.a1, pf.b1, kt + 3);
;     __syncthreads();
; DI void tile_ffn2(const Params& p, int l, const Chunk& ck, int tile, int next, PF& pf, char* smem) {
;   float* Cs = (float*)smem;
;   const int tid = TID(); const int mi = tile & (MTN - 1), ni = tile >> MTS; const int m0 = mi * 128, n0 = ni * 128;
;   f32x16 acc[2][2]; zero_acc(acc);
;   { const u16* Ap; const u16* Wt; ffn2_ptrs(p, l, tile, Ap, Wt); gemm_run<64>(pf, Ap, 4096, Wt, acc, smem); }
.LBB1_206:
	s_add_i32 s25, s26, s78
	s_cmpk_gt_i32 s25, 0x1ff
	s_cselect_b64 s[28:29], -1, 0
	s_cmpk_lt_i32 s25, 0x200
	s_cselect_b32 s0, s25, -1
	s_and_b32 s16, s41, 0x3f80000
	s_and_b32 s36, s26, 0xffffff80
	s_add_i32 s26, s26, s36
	s_lshl_b32 s36, s36, 1
	s_lshl_b32 s16, s16, 1
	s_add_u32 vcc_lo, s17, s16
	v_mov_b32_e32 v0, v172
	s_addc_u32 vcc_hi, s27, 0
	s_ashr_i32 s37, s36, 31
	s_lshl_b64 s[30:31], s[36:37], 6
	s_add_u32 s30, s34, s30
	s_addc_u32 s31, s40, s31
	s_setprio 0
	s_waitcnt lgkmcnt(0)
	s_lshr_b32 s16, s16, 7
	s_add_u32 s42, s17, s16
	s_addc_u32 s43, s27, 0
	v_and_b32_e32 v174, 63, v172
	v_lshrrev_b32_e32 v175, 6, v172
	v_lshrrev_b32_e32 v176, 4, v174
	v_xor_b32_e32 v176, v176, v174
	v_and_b32_e32 v176, 3, v176
	v_lshlrev_b32_e32 v176, 4, v176
	v_lshrrev_b32_e32 v177, 2, v174
	v_lshl_add_u32 v137, v175, 5, v177
	v_lshl_add_u32 v137, v137, 6, v176
	v_mov_b32_e32 v150, v137
	v_lshl_add_u32 v151, v175, 6, v177
	v_lshl_add_u32 v151, v151, 6, v176
	v_mov_b32_e32 v152, v151
	v_mov_b32_e32 v153, v151
	v_mov_b32_e32 v154, v151
	v_readfirstlane_b32 s16, v175
	s_lshl_b32 s0, s16, 12
	s_lshl_b32 s16, s16, 11
	s_add_u32 s0, s0, 0x2000
	v_and_b32_e32 v176, 31, v174
	v_lshrrev_b32_e32 v177, 5, v174
	v_lshrrev_b32_e32 v174, 2, v176
	v_and_b32_e32 v174, 3, v174
	v_xor_b32_e32 v174, v174, v177
	v_lshlrev_b32_e32 v174, 4, v174
	v_lshl_add_u32 v174, v176, 6, v174
	v_lshrrev_b32_e32 v176, 1, v175
	v_and_b32_e32 v177, 1, v175
	v_lshl_add_u32 v126, v176, 12, v174
	v_lshl_add_u32 v128, v177, 12, v174
	v_add_u32_e32 v128, 0x2000, v128
	v_xor_b32_e32 v127, 32, v126
	v_xor_b32_e32 v129, 32, v128
	s_barrier
	v_mov_b32_e32 v34, 0
	v_mov_b32_e32 v35, 0
	v_mov_b32_e32 v36, 0
	v_mov_b32_e32 v37, 0
	v_mov_b32_e32 v38, 0
	v_mov_b32_e32 v39, 0
	v_mov_b32_e32 v40, 0
	v_mov_b32_e32 v41, 0
	v_mov_b32_e32 v42, 0
	v_mov_b32_e32 v43, 0
	v_mov_b32_e32 v44, 0
	v_mov_b32_e32 v45, 0
	v_mov_b32_e32 v46, 0
	v_mov_b32_e32 v47, 0
	v_mov_b32_e32 v48, 0
	v_mov_b32_e32 v49, 0
	v_mov_b32_e32 v50, 0
	v_mov_b32_e32 v51, 0
	v_mov_b32_e32 v52, 0
	v_mov_b32_e32 v53, 0
	v_mov_b32_e32 v54, 0
	v_mov_b32_e32 v55, 0
	v_mov_b32_e32 v56, 0
	v_mov_b32_e32 v57, 0
	v_mov_b32_e32 v58, 0
	v_mov_b32_e32 v59, 0
	v_mov_b32_e32 v60, 0
	v_mov_b32_e32 v61, 0
	v_mov_b32_e32 v62, 0
	v_mov_b32_e32 v63, 0
	v_mov_b32_e32 v64, 0
	v_mov_b32_e32 v65, 0
	v_mov_b32_e32 v2, 0
	v_mov_b32_e32 v3, 0
	v_mov_b32_e32 v4, 0
	v_mov_b32_e32 v5, 0
	v_mov_b32_e32 v6, 0
	v_mov_b32_e32 v7, 0
	v_mov_b32_e32 v8, 0
	v_mov_b32_e32 v9, 0
	v_mov_b32_e32 v10, 0
	v_mov_b32_e32 v11, 0
	v_mov_b32_e32 v12, 0
	v_mov_b32_e32 v13, 0
	v_mov_b32_e32 v14, 0
	v_mov_b32_e32 v15, 0
	v_mov_b32_e32 v16, 0
	v_mov_b32_e32 v17, 0
	v_mov_b32_e32 v18, 0
	v_mov_b32_e32 v19, 0
	v_mov_b32_e32 v20, 0
	v_mov_b32_e32 v21, 0
	v_mov_b32_e32 v22, 0
	v_mov_b32_e32 v23, 0
	v_mov_b32_e32 v24, 0
	v_mov_b32_e32 v25, 0
	v_mov_b32_e32 v26, 0
	v_mov_b32_e32 v27, 0
	v_mov_b32_e32 v28, 0
	v_mov_b32_e32 v29, 0
	v_mov_b32_e32 v30, 0
	v_mov_b32_e32 v31, 0
	v_mov_b32_e32 v32, 0
	v_mov_b32_e32 v33, 0
	v_mov_b32_e32 v74, 0
	v_mov_b32_e32 v75, 0
	v_mov_b32_e32 v76, 0
	v_mov_b32_e32 v77, 0
	v_mov_b32_e32 v78, 0
	v_mov_b32_e32 v79, 0
	v_mov_b32_e32 v80, 0
	v_mov_b32_e32 v81, 0
	v_mov_b32_e32 v82, 0
	v_mov_b32_e32 v83, 0
	v_mov_b32_e32 v84, 0
	v_mov_b32_e32 v85, 0
	v_mov_b32_e32 v86, 0
	v_mov_b32_e32 v87, 0
	v_mov_b32_e32 v88, 0
	v_mov_b32_e32 v89, 0
	v_mov_b32_e32 v90, 0
	v_mov_b32_e32 v91, 0
	v_mov_b32_e32 v92, 0
	v_mov_b32_e32 v93, 0
	v_mov_b32_e32 v94, 0
	v_mov_b32_e32 v95, 0
	v_mov_b32_e32 v96, 0
	v_mov_b32_e32 v97, 0
	v_mov_b32_e32 v98, 0
	v_mov_b32_e32 v99, 0
	v_mov_b32_e32 v100, 0
	v_mov_b32_e32 v101, 0
	v_mov_b32_e32 v102, 0
	v_mov_b32_e32 v103, 0
	v_mov_b32_e32 v104, 0
	v_mov_b32_e32 v105, 0
	v_mov_b32_e32 v106, 0
	v_mov_b32_e32 v107, 0
	v_mov_b32_e32 v108, 0
	v_mov_b32_e32 v109, 0
	v_mov_b32_e32 v110, 0
	v_mov_b32_e32 v111, 0
	v_mov_b32_e32 v112, 0
	v_mov_b32_e32 v113, 0
	v_mov_b32_e32 v114, 0
	v_mov_b32_e32 v115, 0
	v_mov_b32_e32 v116, 0
	v_mov_b32_e32 v117, 0
	v_mov_b32_e32 v118, 0
	v_mov_b32_e32 v119, 0
	v_mov_b32_e32 v120, 0
	v_mov_b32_e32 v121, 0
	v_mov_b32_e32 v208, 0
	v_mov_b32_e32 v209, 0
	v_mov_b32_e32 v210, 0
	v_mov_b32_e32 v211, 0
	v_mov_b32_e32 v212, 0
	v_mov_b32_e32 v213, 0
	v_mov_b32_e32 v214, 0
	v_mov_b32_e32 v215, 0
	v_mov_b32_e32 v216, 0
	v_mov_b32_e32 v217, 0
	v_mov_b32_e32 v218, 0
	v_mov_b32_e32 v219, 0
	v_mov_b32_e32 v220, 0
	v_mov_b32_e32 v221, 0
	v_mov_b32_e32 v222, 0
	v_mov_b32_e32 v223, 0
	s_add_u32 m0, s16, 0x0
	s_nop 0
	global_load_lds_dwordx4 v137, s[42:43]
	global_load_lds_dwordx4 v150, s[42:43] offset:1024
	s_add_u32 m0, s0, 0x0
	s_nop 0
	global_load_lds_dwordx4 v151, s[30:31]
	global_load_lds_dwordx4 v152, s[30:31] offset:1024
	global_load_lds_dwordx4 v153, s[30:31] offset:2048
	global_load_lds_dwordx4 v154, s[30:31] offset:3072
	s_add_u32 m0, s16, 0x6000
	s_add_u32 s42, s42, 0x100000
	s_addc_u32 s43, s43, 0
	global_load_lds_dwordx4 v137, s[42:43]
	global_load_lds_dwordx4 v150, s[42:43] offset:1024
	s_add_u32 m0, s0, 0x6000
	s_add_u32 s30, s30, 0x10000
	s_addc_u32 s31, s31, 0
	global_load_lds_dwordx4 v151, s[30:31]
	global_load_lds_dwordx4 v152, s[30:31] offset:1024
	global_load_lds_dwordx4 v153, s[30:31] offset:2048
	global_load_lds_dwordx4 v154, s[30:31] offset:3072
	s_mov_b32 s46, 42
; #define BLOAD(A_, B_, kt) do { _Pragma("unroll") for (int i = 0; i < 4; ++i) { \
;     A_[i] = *(const u32x4*)((const char*)Ap + (aoff + (unsigned)(32 * i * lda + (kt) * 64) * 2u)); B_[i] = *(const u32x4*)((const char*)Wt + (woff + (unsigned)(32 * i * K + (kt) * 64) * 2u)); } } while (0)
; #define BLOAD(A_, B_, kt) do { _Pragma("unroll") for (int i = 0; i < 4; ++i) { \
;     A_[i] = *(const u32x4*)((const char*)Ap + (aoff + (unsigned)(32 * i * lda + (kt) * 64) * 2u)); B_[i] = *(const u32x4*)((const char*)Wt + (woff + (unsigned)(32 * i * K + (kt) * 64) * 2u)); } } while (0)
; #define BSTORE(A_, B_, buf) do { _Pragma("unroll") for (int i = 0; i < 4; ++i) { \
;     *(u32x4*)&As[(buf) * GBUF + (srow + 32 * i) * LDT + sc8] = A_[i]; \
;     *(u32x4*)&Bs[(buf) * GBUF + (srow + 32 * i) * LDT + sc8] = B_[i]; } } while (0)
; template <int NK>
; DI void gemm_run(PF& pf, const u16* __restrict__ Ap, int lda, const u16* __restrict__ Wt, f32x16 (&acc)[2][2], char* smem) {
;     ...
; #pragma unroll
;   for (int kt = 0; kt < nk; kt += 2) {
;     BCOMP(0);
;     BSTORE(pf.a1, pf.b1, 1);
;     if (kt + 3 < nk) BLOAD(pf.a1, pf.b1, kt + 3);
;     __syncthreads();
;     BCOMP(1);
;     if (kt + 2 < nk) { BSTORE(pf.a0, pf.b0, 0); if (kt + 4 < nk) BLOAD(pf.a0, pf.b0, kt + 4); }
;     __syncthreads();
;   }
.Lffn2_kloop:
	s_waitcnt vmcnt(6)
	s_barrier
	s_setprio 1
	ds_read_b128 v[224:227], v126 offset:0
	ds_read_b128 v[232:235], v128 offset:0
	ds_read_b128 v[236:239], v128 offset:2048
	ds_read_b128 v[228:231], v126 offset:2048
	ds_read_b128 v[240:243], v128 offset:8192
	ds_read_b128 v[244:247], v128 offset:10240
	ds_read_b128 v[248:251], v127 offset:0
	ds_read_b128 v[160:163], v129 offset:0
	ds_read_b128 v[164:167], v129 offset:2048
	ds_read_b128 v[156:159], v127 offset:2048
	ds_read_b128 v[168:171], v129 offset:8192
	ds_read_b128 v[122:125], v129 offset:10240
	s_add_u32 m0, s16, 0xc000
	s_add_u32 s42, s42, 0x100000
	s_addc_u32 s43, s43, 0
	global_load_lds_dwordx4 v137, s[42:43]
	global_load_lds_dwordx4 v150, s[42:43] offset:1024
	s_add_u32 m0, s0, 0xc000
	s_add_u32 s30, s30, 0x10000
	s_addc_u32 s31, s31, 0
	global_load_lds_dwordx4 v151, s[30:31]
	global_load_lds_dwordx4 v152, s[30:31] offset:1024
	global_load_lds_dwordx4 v153, s[30:31] offset:2048
	global_load_lds_dwordx4 v154, s[30:31] offset:3072
	s_waitcnt lgkmcnt(10)
	v_mfma_f32_32x32x16_bf16 v[34:49], v[224:227], v[232:235], v[34:49]
	s_waitcnt lgkmcnt(9)
	v_mfma_f32_32x32x16_bf16 v[50:65], v[224:227], v[236:239], v[50:65]
	s_waitcnt lgkmcnt(8)
	v_mfma_f32_32x32x16_bf16 v[2:17], v[228:231], v[232:235], v[2:17]
	v_mfma_f32_32x32x16_bf16 v[18:33], v[228:231], v[236:239], v[18:33]
	s_waitcnt lgkmcnt(7)
	v_mfma_f32_32x32x16_bf16 v[74:89], v[224:227], v[240:243], v[74:89]
	s_waitcnt lgkmcnt(6)
	v_mfma_f32_32x32x16_bf16 v[90:105], v[224:227], v[244:247], v[90:105]
	v_mfma_f32_32x32x16_bf16 v[106:121], v[228:231], v[240:243], v[106:121]
	v_mfma_f32_32x32x16_bf16 v[208:223], v[228:231], v[244:247], v[208:223]
	s_waitcnt lgkmcnt(4)
	v_mfma_f32_32x32x16_bf16 v[34:49], v[248:251], v[160:163], v[34:49]
	s_waitcnt lgkmcnt(3)
	v_mfma_f32_32x32x16_bf16 v[50:65], v[248:251], v[164:167], v[50:65]
	s_waitcnt lgkmcnt(2)
	v_mfma_f32_32x32x16_bf16 v[2:17], v[156:159], v[160:163], v[2:17]
	v_mfma_f32_32x32x16_bf16 v[18:33], v[156:159], v[164:167], v[18:33]
	s_waitcnt lgkmcnt(1)
	v_mfma_f32_32x32x16_bf16 v[74:89], v[248:251], v[168:171], v[74:89]
	s_waitcnt lgkmcnt(0)
	v_mfma_f32_32x32x16_bf16 v[90:105], v[248:251], v[122:125], v[90:105]
	v_mfma_f32_32x32x16_bf16 v[106:121], v[156:159], v[168:171], v[106:121]
	v_mfma_f32_32x32x16_bf16 v[208:223], v[156:159], v[122:125], v[208:223]
	s_setprio 0
	s_waitcnt vmcnt(6)
	s_barrier
	s_setprio 1
	ds_read_b128 v[224:227], v126 offset:24576
	ds_read_b128 v[232:235], v128 offset:24576
	ds_read_b128 v[236:239], v128 offset:26624
	ds_read_b128 v[228:231], v126 offset:26624
	ds_read_b128 v[240:243], v128 offset:32768
	ds_read_b128 v[244:247], v128 offset:34816
	ds_read_b128 v[248:251], v127 offset:24576
	ds_read_b128 v[160:163], v129 offset:24576
	ds_read_b128 v[164:167], v129 offset:26624
	ds_read_b128 v[156:159], v127 offset:26624
	ds_read_b128 v[168:171], v129 offset:32768
	ds_read_b128 v[122:125], v129 offset:34816
	s_add_u32 m0, s16, 0x0
	s_add_u32 s42, s42, 0x100000
	s_addc_u32 s43, s43, 0
	global_load_lds_dwordx4 v137, s[42:43]
	global_load_lds_dwordx4 v150, s[42:43] offset:1024
	s_add_u32 m0, s0, 0x0
	s_add_u32 s30, s30, 0x10000
	s_addc_u32 s31, s31, 0
	global_load_lds_dwordx4 v151, s[30:31]
	global_load_lds_dwordx4 v152, s[30:31] offset:1024
	global_load_lds_dwordx4 v153, s[30:31] offset:2048
	global_load_lds_dwordx4 v154, s[30:31] offset:3072
	s_waitcnt lgkmcnt(10)
	v_mfma_f32_32x32x16_bf16 v[34:49], v[224:227], v[232:235], v[34:49]
	s_waitcnt lgkmcnt(9)
	v_mfma_f32_32x32x16_bf16 v[50:65], v[224:227], v[236:239], v[50:65]
	s_waitcnt lgkmcnt(8)
	v_mfma_f32_32x32x16_bf16 v[2:17], v[228:231], v[232:235], v[2:17]
	v_mfma_f32_32x32x16_bf16 v[18:33], v[228:231], v[236:239], v[18:33]
	s_waitcnt lgkmcnt(7)
	v_mfma_f32_32x32x16_bf16 v[74:89], v[224:227], v[240:243], v[74:89]
	s_waitcnt lgkmcnt(6)
	v_mfma_f32_32x32x16_bf16 v[90:105], v[224:227], v[244:247], v[90:105]
	v_mfma_f32_32x32x16_bf16 v[106:121], v[228:231], v[240:243], v[106:121]
	v_mfma_f32_32x32x16_bf16 v[208:223], v[228:231], v[244:247], v[208:223]
	s_waitcnt lgkmcnt(4)
	v_mfma_f32_32x32x16_bf16 v[34:49], v[248:251], v[160:163], v[34:49]
	s_waitcnt lgkmcnt(3)
	v_mfma_f32_32x32x16_bf16 v[50:65], v[248:251], v[164:167], v[50:65]
	s_waitcnt lgkmcnt(2)
	v_mfma_f32_32x32x16_bf16 v[2:17], v[156:159], v[160:163], v[2:17]
	v_mfma_f32_32x32x16_bf16 v[18:33], v[156:159], v[164:167], v[18:33]
	s_waitcnt lgkmcnt(1)
	v_mfma_f32_32x32x16_bf16 v[74:89], v[248:251], v[168:171], v[74:89]
	s_waitcnt lgkmcnt(0)
	v_mfma_f32_32x32x16_bf16 v[90:105], v[248:251], v[122:125], v[90:105]
	v_mfma_f32_32x32x16_bf16 v[106:121], v[156:159], v[168:171], v[106:121]
	v_mfma_f32_32x32x16_bf16 v[208:223], v[156:159], v[122:125], v[208:223]
	s_setprio 0
	s_waitcnt vmcnt(6)
	s_barrier
; #define BLOAD(A_, B_, kt) do { _Pragma("unroll") for (int i = 0; i < 4; ++i) { \
;     A_[i] = *(const u32x4*)((const char*)Ap + (aoff + (unsigned)(32 * i * lda + (kt) * 64) * 2u)); B_[i] = *(const u32x4*)((const char*)Wt + (woff + (unsigned)(32 * i * K + (kt) * 64) * 2u)); } } while (0)
; #define BLOAD(A_, B_, kt) do { _Pragma("unroll") for (int i = 0; i < 4; ++i) { \
;     A_[i] = *(const u32x4*)((const char*)Ap + (aoff + (unsigned)(32 * i * lda + (kt) * 64) * 2u)); B_[i] = *(const u32x4*)((const char*)Wt + (woff + (unsigned)(32 * i * K + (kt) * 64) * 2u)); } } while (0)
; #define BSTORE(A_, B_, buf) do { _Pragma("unroll") for (int i = 0; i < 4; ++i) { \
;     *(u32x4*)&As[(buf) * GBUF + (srow + 32 * i) * LDT + sc8] = A_[i]; \
;     *(u32x4*)&Bs[(buf) * GBUF + (srow + 32 * i) * LDT + sc8] = B_[i]; } } while (0)
; template <int NK>
; DI void gemm_run(PF& pf, const u16* __restrict__ Ap, int lda, const u16* __restrict__ Wt, f32x16 (&acc)[2][2], char* smem) {
;     ...
;   __builtin_amdgcn_s_setprio(0);
;   __syncthreads();
;   BSTORE(pf.a0, pf.b0, 0);
;   BLOAD(pf.a0, pf.b0, 2);
;   __syncthreads();
; #pragma unroll
;   for (int kt = 0; kt < nk; kt += 2) {
;     BCOMP(0);
;     BSTORE(pf.a1, pf.b1, 1);
;     if (kt + 3 < nk) BLOAD(pf.a1, pf.b1, kt + 3);
;     __syncthreads();
;     BCOMP(1);
;     if (kt + 2 < nk) { BSTORE(pf.a0, pf.b0, 0); if (kt + 4 < nk) BLOAD(pf.a0, pf.b0, kt + 4); }
;     __syncthreads();
	s_setprio 1
	ds_read_b128 v[224:227], v126 offset:49152
	ds_read_b128 v[232:235], v128 offset:49152
	ds_read_b128 v[236:239], v128 offset:51200
	ds_read_b128 v[228:231], v126 offset:51200
	ds_read_b128 v[240:243], v128 offset:57344
	ds_read_b128 v[244:247], v128 offset:59392
	ds_read_b128 v[248:251], v127 offset:49152
	ds_read_b128 v[160:163], v129 offset:49152
	ds_read_b128 v[164:167], v129 offset:51200
	ds_read_b128 v[156:159], v127 offset:51200
	ds_read_b128 v[168:171], v129 offset:57344
	ds_read_b128 v[122:125], v129 offset:59392
	s_add_u32 m0, s16, 0x6000
	s_add_u32 s42, s42, 0x100000
	s_addc_u32 s43, s43, 0
	global_load_lds_dwordx4 v137, s[42:43]
	global_load_lds_dwordx4 v150, s[42:43] offset:1024
	s_add_u32 m0, s0, 0x6000
	s_add_u32 s30, s30, 0x10000
	s_addc_u32 s31, s31, 0
	global_load_lds_dwordx4 v151, s[30:31]
	global_load_lds_dwordx4 v152, s[30:31] offset:1024
	global_load_lds_dwordx4 v153, s[30:31] offset:2048
	global_load_lds_dwordx4 v154, s[30:31] offset:3072
	s_waitcnt lgkmcnt(10)
	v_mfma_f32_32x32x16_bf16 v[34:49], v[224:227], v[232:235], v[34:49]
	s_waitcnt lgkmcnt(9)
	v_mfma_f32_32x32x16_bf16 v[50:65], v[224:227], v[236:239], v[50:65]
	s_waitcnt lgkmcnt(8)
	v_mfma_f32_32x32x16_bf16 v[2:17], v[228:231], v[232:235], v[2:17]
	v_mfma_f32_32x32x16_bf16 v[18:33], v[228:231], v[236:239], v[18:33]
	s_waitcnt lgkmcnt(7)
	v_mfma_f32_32x32x16_bf16 v[74:89], v[224:227], v[240:243], v[74:89]
	s_waitcnt lgkmcnt(6)
	v_mfma_f32_32x32x16_bf16 v[90:105], v[224:227], v[244:247], v[90:105]
	v_mfma_f32_32x32x16_bf16 v[106:121], v[228:231], v[240:243], v[106:121]
	v_mfma_f32_32x32x16_bf16 v[208:223], v[228:231], v[244:247], v[208:223]
	s_waitcnt lgkmcnt(4)
	v_mfma_f32_32x32x16_bf16 v[34:49], v[248:251], v[160:163], v[34:49]
	s_waitcnt lgkmcnt(3)
	v_mfma_f32_32x32x16_bf16 v[50:65], v[248:251], v[164:167], v[50:65]
	s_waitcnt lgkmcnt(2)
	v_mfma_f32_32x32x16_bf16 v[2:17], v[156:159], v[160:163], v[2:17]
	v_mfma_f32_32x32x16_bf16 v[18:33], v[156:159], v[164:167], v[18:33]
	s_waitcnt lgkmcnt(1)
	v_mfma_f32_32x32x16_bf16 v[74:89], v[248:251], v[168:171], v[74:89]
	s_waitcnt lgkmcnt(0)
	v_mfma_f32_32x32x16_bf16 v[90:105], v[248:251], v[122:125], v[90:105]
	v_mfma_f32_32x32x16_bf16 v[106:121], v[156:159], v[168:171], v[106:121]
	v_mfma_f32_32x32x16_bf16 v[208:223], v[156:159], v[122:125], v[208:223]
	s_setprio 0
	s_sub_u32 s46, s46, 1
	s_cmp_lg_u32 s46, 0
	s_cbranch_scc1 .Lffn2_kloop
	s_waitcnt vmcnt(6)
	s_barrier
	s_setprio 1
	ds_read_b128 v[224:227], v126 offset:0
	ds_read_b128 v[232:235], v128 offset:0
	ds_read_b128 v[236:239], v128 offset:2048
	ds_read_b128 v[228:231], v126 offset:2048
	ds_read_b128 v[240:243], v128 offset:8192
	ds_read_b128 v[244:247], v128 offset:10240
	ds_read_b128 v[248:251], v127 offset:0
	ds_read_b128 v[160:163], v129 offset:0
	ds_read_b128 v[164:167], v129 offset:2048
	ds_read_b128 v[156:159], v127 offset:2048
	ds_read_b128 v[168:171], v129 offset:8192
	ds_read_b128 v[122:125], v129 offset:10240
	s_waitcnt lgkmcnt(10)
	v_mfma_f32_32x32x16_bf16 v[34:49], v[224:227], v[232:235], v[34:49]
	s_waitcnt lgkmcnt(9)
	v_mfma_f32_32x32x16_bf16 v[50:65], v[224:227], v[236:239], v[50:65]
	s_waitcnt lgkmcnt(8)
	v_mfma_f32_32x32x16_bf16 v[2:17], v[228:231], v[232:235], v[2:17]
	v_mfma_f32_32x32x16_bf16 v[18:33], v[228:231], v[236:239], v[18:33]
	s_waitcnt lgkmcnt(7)
	v_mfma_f32_32x32x16_bf16 v[74:89], v[224:227], v[240:243], v[74:89]
	s_waitcnt lgkmcnt(6)
	v_mfma_f32_32x32x16_bf16 v[90:105], v[224:227], v[244:247], v[90:105]
	v_mfma_f32_32x32x16_bf16 v[106:121], v[228:231], v[240:243], v[106:121]
	v_mfma_f32_32x32x16_bf16 v[208:223], v[228:231], v[244:247], v[208:223]
	s_waitcnt lgkmcnt(4)
	v_mfma_f32_32x32x16_bf16 v[34:49], v[248:251], v[160:163], v[34:49]
	s_waitcnt lgkmcnt(3)
	v_mfma_f32_32x32x16_bf16 v[50:65], v[248:251], v[164:167], v[50:65]
	s_waitcnt lgkmcnt(2)
	v_mfma_f32_32x32x16_bf16 v[2:17], v[156:159], v[160:163], v[2:17]
	v_mfma_f32_32x32x16_bf16 v[18:33], v[156:159], v[164:167], v[18:33]
	s_waitcnt lgkmcnt(1)
	v_mfma_f32_32x32x16_bf16 v[74:89], v[248:251], v[168:171], v[74:89]
	s_waitcnt lgkmcnt(0)
	v_mfma_f32_32x32x16_bf16 v[90:105], v[248:251], v[122:125], v[90:105]
	v_mfma_f32_32x32x16_bf16 v[106:121], v[156:159], v[168:171], v[106:121]
	v_mfma_f32_32x32x16_bf16 v[208:223], v[156:159], v[122:125], v[208:223]
	s_setprio 0
	s_waitcnt vmcnt(0)
	s_barrier
	s_setprio 1
	ds_read_b128 v[224:227], v126 offset:24576
	ds_read_b128 v[232:235], v128 offset:24576
	ds_read_b128 v[236:239], v128 offset:26624
	ds_read_b128 v[228:231], v126 offset:26624
	ds_read_b128 v[240:243], v128 offset:32768
	ds_read_b128 v[244:247], v128 offset:34816
	ds_read_b128 v[248:251], v127 offset:24576
	ds_read_b128 v[160:163], v129 offset:24576
	ds_read_b128 v[164:167], v129 offset:26624
	ds_read_b128 v[156:159], v127 offset:26624
	ds_read_b128 v[168:171], v129 offset:32768
	ds_read_b128 v[122:125], v129 offset:34816
	s_waitcnt lgkmcnt(10)
	v_mfma_f32_32x32x16_bf16 v[34:49], v[224:227], v[232:235], v[34:49]
	s_waitcnt lgkmcnt(9)
	v_mfma_f32_32x32x16_bf16 v[50:65], v[224:227], v[236:239], v[50:65]
	s_waitcnt lgkmcnt(8)
	v_mfma_f32_32x32x16_bf16 v[2:17], v[228:231], v[232:235], v[2:17]
	v_mfma_f32_32x32x16_bf16 v[18:33], v[228:231], v[236:239], v[18:33]
	s_waitcnt lgkmcnt(7)
	v_mfma_f32_32x32x16_bf16 v[74:89], v[224:227], v[240:243], v[74:89]
	s_waitcnt lgkmcnt(6)
	v_mfma_f32_32x32x16_bf16 v[90:105], v[224:227], v[244:247], v[90:105]
	v_mfma_f32_32x32x16_bf16 v[106:121], v[228:231], v[240:243], v[106:121]
	v_mfma_f32_32x32x16_bf16 v[208:223], v[228:231], v[244:247], v[208:223]
	s_waitcnt lgkmcnt(4)
	v_mfma_f32_32x32x16_bf16 v[34:49], v[248:251], v[160:163], v[34:49]
	s_waitcnt lgkmcnt(3)
	v_mfma_f32_32x32x16_bf16 v[50:65], v[248:251], v[164:167], v[50:65]
	s_waitcnt lgkmcnt(2)
	v_mfma_f32_32x32x16_bf16 v[2:17], v[156:159], v[160:163], v[2:17]
	v_mfma_f32_32x32x16_bf16 v[18:33], v[156:159], v[164:167], v[18:33]
	s_waitcnt lgkmcnt(1)
	v_mfma_f32_32x32x16_bf16 v[74:89], v[248:251], v[168:171], v[74:89]
	s_waitcnt lgkmcnt(0)
	v_mfma_f32_32x32x16_bf16 v[90:105], v[248:251], v[122:125], v[90:105]
	v_mfma_f32_32x32x16_bf16 v[106:121], v[156:159], v[168:171], v[106:121]
	v_mfma_f32_32x32x16_bf16 v[208:223], v[156:159], v[122:125], v[208:223]
	s_setprio 0
	s_barrier
	s_mov_b32 s16, 0

; DI int TID() { int t = (int)__builtin_amdgcn_workitem_id_x(); asm volatile("" : "+v"(t)); return t; }
; DI RowSS rowss_load(const float* ps, int m0) { const int tid = TID(); const float* q = ps + (size_t)(m0 + (tid >> 1)) * 16 + (tid & 1) * 8; RowSS r; r.a = *(const f32x4*)q; r.b = *(const f32x4*)(q + 4); return r; }
; DI void zero_acc(f32x16 (&acc)[2][2]) {
; #pragma unroll
;   for (int a = 0; a < 2; ++a)
; #pragma unroll
;     for (int b = 0; b < 2; ++b)
; #pragma unroll
;       for (int r = 0; r < 16; ++r) acc[a][b][r] = 0.f;
; }
; DI void tile_ffn1(const Params& p, int l, const Chunk& ck, int tile, int next, PF& pf, char* smem) {
;   float* Cs = (float*)smem; float* rinv_s = (float*)(smem + SMEM_CS);
;   const int tid = TID(); const int mi = tile & (MTN - 1), ni = tile >> MTS; const int m0 = mi * 128, n0 = ni * 128;
;   f32x16 acc[2][2]; zero_acc(acc);
;   const RowSS rss = rowss_load((const float*)(p.ws + OFF_PSMID), m0);
;   { const u16* Ap; const u16* Wt; ffn1_ptrs(p, l, tile, Ap, Wt); gemm_run<16>(pf, Ap, 1024, Wt, acc, smem); }
;   if (next >= 0) { const u16* An; const u16* Wn; ffn1_ptrs(p, l, next, An, Wn); gemm_issue(pf, An, 1024, Wn, 1024); }
.LBB1_246:
	s_mov_b32 s26, s16
	s_add_i32 s16, s16, s78
	s_cmpk_gt_i32 s16, 0x7ff
	s_cselect_b64 s[24:25], -1, 0
	s_cmpk_lt_i32 s16, 0x800
	v_mov_b32_e32 v148, v172
	v_mov_b32_e32 v0, v172
	s_cselect_b32 s0, s16, -1
	s_and_b32 s41, s40, 0x3f80
	s_and_b32 s27, s35, 0xfe0000
	v_ashrrev_i32_e32 v2, 1, v0
	v_add_u32_e32 v2, s41, v2
	v_ashrrev_i32_e32 v3, 31, v2
	v_lshlrev_b64 v[2:3], 6, v[2:3]
	v_lshlrev_b32_e32 v0, 5, v0
	v_lshl_add_u64 v[2:3], s[20:21], 0, v[2:3]
	v_and_b32_e32 v0, 32, v0
	v_lshl_add_u64 v[2:3], v[2:3], 0, v[0:1]
	global_load_dwordx4 v[66:69], v[2:3], off offset:16
	global_load_dwordx4 v[70:73], v[2:3], off
	s_and_b32 s26, s26, 0xffffff80
	s_lshl_b32 s26, s26, 1
	s_lshl_b32 s27, s27, 1
	s_add_u32 s28, s17, s27
	s_addc_u32 s29, s34, 0
	s_ashr_i32 s27, s26, 31
	s_lshl_b64 s[30:31], s[26:27], 6
	s_add_u32 s30, s36, s30
	s_addc_u32 s31, s37, s31
	s_setprio 0
	s_waitcnt lgkmcnt(0)
	s_mov_b32 s0, 0
	v_and_b32_e32 v149, 63, v172
	v_lshrrev_b32_e32 v151, 6, v172
	v_lshrrev_b32_e32 v152, 4, v149
	v_xor_b32_e32 v152, v152, v149
	v_and_b32_e32 v152, 3, v152
	v_lshlrev_b32_e32 v152, 4, v152
	v_lshrrev_b32_e32 v153, 2, v149
	v_lshl_add_u32 v142, v151, 5, v153
	v_lshl_add_u32 v142, v142, 11, v152
	v_add_u32_e32 v143, 0x7c00, v142
	v_lshl_add_u32 v144, v151, 6, v153
	v_lshl_add_u32 v144, v144, 6, v152
	v_mov_b32_e32 v145, v144
	v_mov_b32_e32 v146, v144
	v_mov_b32_e32 v147, v144
	v_readfirstlane_b32 s42, v151
	s_lshl_b32 s43, s42, 12
	s_lshl_b32 s42, s42, 11
	s_add_u32 s43, s43, 0x2000
	v_and_b32_e32 v152, 31, v149
	v_lshrrev_b32_e32 v153, 5, v149
	v_lshrrev_b32_e32 v149, 2, v152
	v_and_b32_e32 v149, 3, v149
	v_xor_b32_e32 v149, v149, v153
	v_lshlrev_b32_e32 v149, 4, v149
	v_lshl_add_u32 v149, v152, 6, v149
	v_lshrrev_b32_e32 v152, 1, v151
	v_and_b32_e32 v153, 1, v151
	v_lshl_add_u32 v138, v152, 12, v149
	v_lshl_add_u32 v140, v153, 12, v149
	v_add_u32_e32 v140, 0x2000, v140
	v_xor_b32_e32 v139, 32, v138
	v_xor_b32_e32 v141, 32, v140
	s_barrier
	v_mov_b32_e32 v34, 0
	v_mov_b32_e32 v35, 0
	v_mov_b32_e32 v36, 0
	v_mov_b32_e32 v37, 0
	v_mov_b32_e32 v38, 0
	v_mov_b32_e32 v39, 0
	v_mov_b32_e32 v40, 0
	v_mov_b32_e32 v41, 0
	v_mov_b32_e32 v42, 0
	v_mov_b32_e32 v43, 0
	v_mov_b32_e32 v44, 0
	v_mov_b32_e32 v45, 0
	v_mov_b32_e32 v46, 0
	v_mov_b32_e32 v47, 0
	v_mov_b32_e32 v48, 0
	v_mov_b32_e32 v49, 0
	v_mov_b32_e32 v50, 0
	v_mov_b32_e32 v51, 0
	v_mov_b32_e32 v52, 0
	v_mov_b32_e32 v53, 0
	v_mov_b32_e32 v54, 0
	v_mov_b32_e32 v55, 0
	v_mov_b32_e32 v56, 0
	v_mov_b32_e32 v57, 0
	v_mov_b32_e32 v58, 0
	v_mov_b32_e32 v59, 0
	v_mov_b32_e32 v60, 0
	v_mov_b32_e32 v61, 0
	v_mov_b32_e32 v62, 0
	v_mov_b32_e32 v63, 0
	v_mov_b32_e32 v64, 0
	v_mov_b32_e32 v65, 0
	v_mov_b32_e32 v2, 0
	v_mov_b32_e32 v3, 0
	v_mov_b32_e32 v4, 0
	v_mov_b32_e32 v5, 0
	v_mov_b32_e32 v6, 0
	v_mov_b32_e32 v7, 0
	v_mov_b32_e32 v8, 0
	v_mov_b32_e32 v9, 0
	v_mov_b32_e32 v10, 0
	v_mov_b32_e32 v11, 0
	v_mov_b32_e32 v12, 0
	v_mov_b32_e32 v13, 0
	v_mov_b32_e32 v14, 0
	v_mov_b32_e32 v15, 0
	v_mov_b32_e32 v16, 0
	v_mov_b32_e32 v17, 0
	v_mov_b32_e32 v18, 0
	v_mov_b32_e32 v19, 0
	v_mov_b32_e32 v20, 0
	v_mov_b32_e32 v21, 0
	v_mov_b32_e32 v22, 0
	v_mov_b32_e32 v23, 0
	v_mov_b32_e32 v24, 0
	v_mov_b32_e32 v25, 0
	v_mov_b32_e32 v26, 0
	v_mov_b32_e32 v27, 0
	v_mov_b32_e32 v28, 0
	v_mov_b32_e32 v29, 0
	v_mov_b32_e32 v30, 0
	v_mov_b32_e32 v31, 0
	v_mov_b32_e32 v32, 0
	v_mov_b32_e32 v33, 0
	v_mov_b32_e32 v74, 0
	v_mov_b32_e32 v75, 0
	v_mov_b32_e32 v76, 0
	v_mov_b32_e32 v77, 0
	v_mov_b32_e32 v78, 0
	v_mov_b32_e32 v79, 0
	v_mov_b32_e32 v80, 0
	v_mov_b32_e32 v81, 0
	v_mov_b32_e32 v82, 0
	v_mov_b32_e32 v83, 0
	v_mov_b32_e32 v84, 0
	v_mov_b32_e32 v85, 0
	v_mov_b32_e32 v86, 0
	v_mov_b32_e32 v87, 0
	v_mov_b32_e32 v88, 0
	v_mov_b32_e32 v89, 0
	v_mov_b32_e32 v90, 0
	v_mov_b32_e32 v91, 0
	v_mov_b32_e32 v92, 0
	v_mov_b32_e32 v93, 0
	v_mov_b32_e32 v94, 0
	v_mov_b32_e32 v95, 0
	v_mov_b32_e32 v96, 0
	v_mov_b32_e32 v97, 0
	v_mov_b32_e32 v98, 0
	v_mov_b32_e32 v99, 0
	v_mov_b32_e32 v100, 0
	v_mov_b32_e32 v101, 0
	v_mov_b32_e32 v102, 0
	v_mov_b32_e32 v103, 0
	v_mov_b32_e32 v104, 0
	v_mov_b32_e32 v105, 0
	v_mov_b32_e32 v106, 0
	v_mov_b32_e32 v107, 0
	v_mov_b32_e32 v108, 0
	v_mov_b32_e32 v109, 0
	v_mov_b32_e32 v110, 0
	v_mov_b32_e32 v111, 0
	v_mov_b32_e32 v112, 0
	v_mov_b32_e32 v113, 0
	v_mov_b32_e32 v114, 0
	v_mov_b32_e32 v115, 0
	v_mov_b32_e32 v116, 0
	v_mov_b32_e32 v117, 0
	v_mov_b32_e32 v118, 0
	v_mov_b32_e32 v119, 0
	v_mov_b32_e32 v120, 0
	v_mov_b32_e32 v121, 0
	v_mov_b32_e32 v122, 0
	v_mov_b32_e32 v123, 0
	v_mov_b32_e32 v124, 0
	v_mov_b32_e32 v125, 0
	v_mov_b32_e32 v126, 0
	v_mov_b32_e32 v127, 0
	v_mov_b32_e32 v128, 0
	v_mov_b32_e32 v129, 0
	v_mov_b32_e32 v130, 0
	v_mov_b32_e32 v131, 0
	v_mov_b32_e32 v132, 0
	v_mov_b32_e32 v133, 0
	v_mov_b32_e32 v134, 0
	v_mov_b32_e32 v135, 0
	v_mov_b32_e32 v136, 0
	v_mov_b32_e32 v137, 0
	s_add_u32 m0, s42, 0x0
	s_nop 0
	global_load_lds_dwordx4 v142, s[28:29]
	global_load_lds_dwordx4 v143, s[28:29] offset:1024
	s_add_u32 m0, s43, 0x0
	s_nop 0
	global_load_lds_dwordx4 v144, s[30:31]
	global_load_lds_dwordx4 v145, s[30:31] offset:1024
	global_load_lds_dwordx4 v146, s[30:31] offset:2048
	global_load_lds_dwordx4 v147, s[30:31] offset:3072
	s_add_u32 m0, s42, 0x6000
	s_add_u32 s28, s28, 0x40
	s_addc_u32 s29, s29, 0
	global_load_lds_dwordx4 v142, s[28:29]
	global_load_lds_dwordx4 v143, s[28:29] offset:1024
	s_add_u32 m0, s43, 0x6000
	s_add_u32 s30, s30, 0x40000
	s_addc_u32 s31, s31, 0
	global_load_lds_dwordx4 v144, s[30:31]
	global_load_lds_dwordx4 v145, s[30:31] offset:1024
	global_load_lds_dwordx4 v146, s[30:31] offset:2048
	global_load_lds_dwordx4 v147, s[30:31] offset:3072
	s_mov_b32 s46, 10
; #define BLOAD(A_, B_, kt) do { _Pragma("unroll") for (int i = 0; i < 4; ++i) { \
;     A_[i] = *(const u32x4*)((const char*)Ap + (aoff + (unsigned)(32 * i * lda + (kt) * 64) * 2u)); B_[i] = *(const u32x4*)((const char*)Wt + (woff + (unsigned)(32 * i * K + (kt) * 64) * 2u)); } } while (0)
; #define BLOAD(A_, B_, kt) do { _Pragma("unroll") for (int i = 0; i < 4; ++i) { \
;     A_[i] = *(const u32x4*)((const char*)Ap + (aoff + (unsigned)(32 * i * lda + (kt) * 64) * 2u)); B_[i] = *(const u32x4*)((const char*)Wt + (woff + (unsigned)(32 * i * K + (kt) * 64) * 2u)); } } while (0)
; #define BSTORE(A_, B_, buf) do { _Pragma("unroll") for (int i = 0; i < 4; ++i) { \
;     *(u32x4*)&As[(buf) * GBUF + (srow + 32 * i) * LDT + sc8] = A_[i]; \
;     *(u32x4*)&Bs[(buf) * GBUF + (srow + 32 * i) * LDT + sc8] = B_[i]; } } while (0)
; template <int NK>
; DI void gemm_run(PF& pf, const u16* __restrict__ Ap, int lda, const u16* __restrict__ Wt, f32x16 (&acc)[2][2], char* smem) {
;     ...
;   __builtin_amdgcn_s_setprio(0);
;   __syncthreads();
;   BSTORE(pf.a0, pf.b0, 0);
;   BLOAD(pf.a0, pf.b0, 2);
;   __syncthreads();
; #pragma unroll
;   for (int kt = 0; kt < nk; kt += 2) {
;     BCOMP(0);
;     BSTORE(pf.a1, pf.b1, 1);
;     if (kt + 3 < nk) BLOAD(pf.a1, pf.b1, kt + 3);
;     __syncthreads();
;     BCOMP(1);
;     if (kt + 2 < nk) { BSTORE(pf.a0, pf.b0, 0); if (kt + 4 < nk) BLOAD(pf.a0, pf.b0, kt + 4); }
;     __syncthreads();
.Lffn1_kloop:
	s_waitcnt vmcnt(6)
	s_barrier
	s_setprio 1
	ds_read_b128 v[208:211], v138 offset:0
	ds_read_b128 v[216:219], v140 offset:0
	ds_read_b128 v[220:223], v140 offset:2048
	ds_read_b128 v[212:215], v138 offset:2048
	ds_read_b128 v[224:227], v140 offset:8192
	ds_read_b128 v[228:231], v140 offset:10240
	ds_read_b128 v[232:235], v139 offset:0
	ds_read_b128 v[240:243], v141 offset:0
	ds_read_b128 v[244:247], v141 offset:2048
	ds_read_b128 v[236:239], v139 offset:2048
	ds_read_b128 v[248:251], v141 offset:8192
	ds_read_b128 v[156:159], v141 offset:10240
	s_add_u32 m0, s42, 0xc000
	s_add_u32 s28, s28, 0x40
	s_addc_u32 s29, s29, 0
	global_load_lds_dwordx4 v142, s[28:29]
	global_load_lds_dwordx4 v143, s[28:29] offset:1024
	s_add_u32 m0, s43, 0xc000
	s_add_u32 s30, s30, 0x40000
	s_addc_u32 s31, s31, 0
	global_load_lds_dwordx4 v144, s[30:31]
	global_load_lds_dwordx4 v145, s[30:31] offset:1024
	global_load_lds_dwordx4 v146, s[30:31] offset:2048
	global_load_lds_dwordx4 v147, s[30:31] offset:3072
	s_waitcnt lgkmcnt(10)
	v_mfma_f32_32x32x16_bf16 v[34:49], v[208:211], v[216:219], v[34:49]
	s_waitcnt lgkmcnt(9)
	v_mfma_f32_32x32x16_bf16 v[50:65], v[208:211], v[220:223], v[50:65]
	s_waitcnt lgkmcnt(8)
	v_mfma_f32_32x32x16_bf16 v[2:17], v[212:215], v[216:219], v[2:17]
	v_mfma_f32_32x32x16_bf16 v[18:33], v[212:215], v[220:223], v[18:33]
	s_waitcnt lgkmcnt(7)
	v_mfma_f32_32x32x16_bf16 v[74:89], v[208:211], v[224:227], v[74:89]
	s_waitcnt lgkmcnt(6)
	v_mfma_f32_32x32x16_bf16 v[90:105], v[208:211], v[228:231], v[90:105]
	v_mfma_f32_32x32x16_bf16 v[106:121], v[212:215], v[224:227], v[106:121]
	v_mfma_f32_32x32x16_bf16 v[122:137], v[212:215], v[228:231], v[122:137]
	s_waitcnt lgkmcnt(4)
	v_mfma_f32_32x32x16_bf16 v[34:49], v[232:235], v[240:243], v[34:49]
	s_waitcnt lgkmcnt(3)
	v_mfma_f32_32x32x16_bf16 v[50:65], v[232:235], v[244:247], v[50:65]
	s_waitcnt lgkmcnt(2)
	v_mfma_f32_32x32x16_bf16 v[2:17], v[236:239], v[240:243], v[2:17]
	v_mfma_f32_32x32x16_bf16 v[18:33], v[236:239], v[244:247], v[18:33]
	s_waitcnt lgkmcnt(1)
	v_mfma_f32_32x32x16_bf16 v[74:89], v[232:235], v[248:251], v[74:89]
	s_waitcnt lgkmcnt(0)
	v_mfma_f32_32x32x16_bf16 v[90:105], v[232:235], v[156:159], v[90:105]
	v_mfma_f32_32x32x16_bf16 v[106:121], v[236:239], v[248:251], v[106:121]
	v_mfma_f32_32x32x16_bf16 v[122:137], v[236:239], v[156:159], v[122:137]
	s_setprio 0
	s_waitcnt vmcnt(6)
	s_barrier
	s_setprio 1
	ds_read_b128 v[208:211], v138 offset:24576
	ds_read_b128 v[216:219], v140 offset:24576
	ds_read_b128 v[220:223], v140 offset:26624
	ds_read_b128 v[212:215], v138 offset:26624
	ds_read_b128 v[224:227], v140 offset:32768
	ds_read_b128 v[228:231], v140 offset:34816
	ds_read_b128 v[232:235], v139 offset:24576
	ds_read_b128 v[240:243], v141 offset:24576
	ds_read_b128 v[244:247], v141 offset:26624
	ds_read_b128 v[236:239], v139 offset:26624
	ds_read_b128 v[248:251], v141 offset:32768
	ds_read_b128 v[156:159], v141 offset:34816
	s_add_u32 m0, s42, 0x0
	s_add_u32 s28, s28, 0x40
	s_addc_u32 s29, s29, 0
	global_load_lds_dwordx4 v142, s[28:29]
	global_load_lds_dwordx4 v143, s[28:29] offset:1024
	s_add_u32 m0, s43, 0x0
	s_add_u32 s30, s30, 0x40000
	s_addc_u32 s31, s31, 0
	global_load_lds_dwordx4 v144, s[30:31]
	global_load_lds_dwordx4 v145, s[30:31] offset:1024
	global_load_lds_dwordx4 v146, s[30:31] offset:2048
	global_load_lds_dwordx4 v147, s[30:31] offset:3072
	s_waitcnt lgkmcnt(10)
	v_mfma_f32_32x32x16_bf16 v[34:49], v[208:211], v[216:219], v[34:49]
	s_waitcnt lgkmcnt(9)
	v_mfma_f32_32x32x16_bf16 v[50:65], v[208:211], v[220:223], v[50:65]
	s_waitcnt lgkmcnt(8)
	v_mfma_f32_32x32x16_bf16 v[2:17], v[212:215], v[216:219], v[2:17]
	v_mfma_f32_32x32x16_bf16 v[18:33], v[212:215], v[220:223], v[18:33]
	s_waitcnt lgkmcnt(7)
	v_mfma_f32_32x32x16_bf16 v[74:89], v[208:211], v[224:227], v[74:89]
	s_waitcnt lgkmcnt(6)
	v_mfma_f32_32x32x16_bf16 v[90:105], v[208:211], v[228:231], v[90:105]
	v_mfma_f32_32x32x16_bf16 v[106:121], v[212:215], v[224:227], v[106:121]
	v_mfma_f32_32x32x16_bf16 v[122:137], v[212:215], v[228:231], v[122:137]
	s_waitcnt lgkmcnt(4)
	v_mfma_f32_32x32x16_bf16 v[34:49], v[232:235], v[240:243], v[34:49]
	s_waitcnt lgkmcnt(3)
	v_mfma_f32_32x32x16_bf16 v[50:65], v[232:235], v[244:247], v[50:65]
	s_waitcnt lgkmcnt(2)
	v_mfma_f32_32x32x16_bf16 v[2:17], v[236:239], v[240:243], v[2:17]
	v_mfma_f32_32x32x16_bf16 v[18:33], v[236:239], v[244:247], v[18:33]
	s_waitcnt lgkmcnt(1)
	v_mfma_f32_32x32x16_bf16 v[74:89], v[232:235], v[248:251], v[74:89]
	s_waitcnt lgkmcnt(0)
	v_mfma_f32_32x32x16_bf16 v[90:105], v[232:235], v[156:159], v[90:105]
	v_mfma_f32_32x32x16_bf16 v[106:121], v[236:239], v[248:251], v[106:121]
	v_mfma_f32_32x32x16_bf16 v[122:137], v[236:239], v[156:159], v[122:137]
	s_setprio 0
	s_waitcnt vmcnt(6)
	s_barrier
; #define BLOAD(A_, B_, kt) do { _Pragma("unroll") for (int i = 0; i < 4; ++i) { \
;     A_[i] = *(const u32x4*)((const char*)Ap + (aoff + (unsigned)(32 * i * lda + (kt) * 64) * 2u)); B_[i] = *(const u32x4*)((const char*)Wt + (woff + (unsigned)(32 * i * K + (kt) * 64) * 2u)); } } while (0)
; #define BLOAD(A_, B_, kt) do { _Pragma("unroll") for (int i = 0; i < 4; ++i) { \
;     A_[i] = *(const u32x4*)((const char*)Ap + (aoff + (unsigned)(32 * i * lda + (kt) * 64) * 2u)); B_[i] = *(const u32x4*)((const char*)Wt + (woff + (unsigned)(32 * i * K + (kt) * 64) * 2u)); } } while (0)
; #define BSTORE(A_, B_, buf) do { _Pragma("unroll") for (int i = 0; i < 4; ++i) { \
;     *(u32x4*)&As[(buf) * GBUF + (srow + 32 * i) * LDT + sc8] = A_[i]; \
;     *(u32x4*)&Bs[(buf) * GBUF + (srow + 32 * i) * LDT + sc8] = B_[i]; } } while (0)
; template <int NK>
; DI void gemm_run(PF& pf, const u16* __restrict__ Ap, int lda, const u16* __restrict__ Wt, f32x16 (&acc)[2][2], char* smem) {
;     ...
;   __builtin_amdgcn_s_setprio(0);
;   __syncthreads();
;   BSTORE(pf.a0, pf.b0, 0);
;   BLOAD(pf.a0, pf.b0, 2);
;   __syncthreads();
; #pragma unroll
;   for (int kt = 0; kt < nk; kt += 2) {
;     BCOMP(0);
;     BSTORE(pf.a1, pf.b1, 1);
;     if (kt + 3 < nk) BLOAD(pf.a1, pf.b1, kt + 3);
;     __syncthreads();
;     BCOMP(1);
;     if (kt + 2 < nk) { BSTORE(pf.a0, pf.b0, 0); if (kt + 4 < nk) BLOAD(pf.a0, pf.b0, kt + 4); }
;     __syncthreads();
	s_setprio 1
	ds_read_b128 v[208:211], v138 offset:49152
	ds_read_b128 v[216:219], v140 offset:49152
	ds_read_b128 v[220:223], v140 offset:51200
	ds_read_b128 v[212:215], v138 offset:51200
	ds_read_b128 v[224:227], v140 offset:57344
	ds_read_b128 v[228:231], v140 offset:59392
	ds_read_b128 v[232:235], v139 offset:49152
	ds_read_b128 v[240:243], v141 offset:49152
	ds_read_b128 v[244:247], v141 offset:51200
	ds_read_b128 v[236:239], v139 offset:51200
	ds_read_b128 v[248:251], v141 offset:57344
	ds_read_b128 v[156:159], v141 offset:59392
	s_add_u32 m0, s42, 0x6000
	s_add_u32 s28, s28, 0x40
	s_addc_u32 s29, s29, 0
	global_load_lds_dwordx4 v142, s[28:29]
	global_load_lds_dwordx4 v143, s[28:29] offset:1024
	s_add_u32 m0, s43, 0x6000
	s_add_u32 s30, s30, 0x40000
	s_addc_u32 s31, s31, 0
	global_load_lds_dwordx4 v144, s[30:31]
	global_load_lds_dwordx4 v145, s[30:31] offset:1024
	global_load_lds_dwordx4 v146, s[30:31] offset:2048
	global_load_lds_dwordx4 v147, s[30:31] offset:3072
	s_waitcnt lgkmcnt(10)
	v_mfma_f32_32x32x16_bf16 v[34:49], v[208:211], v[216:219], v[34:49]
	s_waitcnt lgkmcnt(9)
	v_mfma_f32_32x32x16_bf16 v[50:65], v[208:211], v[220:223], v[50:65]
	s_waitcnt lgkmcnt(8)
	v_mfma_f32_32x32x16_bf16 v[2:17], v[212:215], v[216:219], v[2:17]
	v_mfma_f32_32x32x16_bf16 v[18:33], v[212:215], v[220:223], v[18:33]
	s_waitcnt lgkmcnt(7)
	v_mfma_f32_32x32x16_bf16 v[74:89], v[208:211], v[224:227], v[74:89]
	s_waitcnt lgkmcnt(6)
	v_mfma_f32_32x32x16_bf16 v[90:105], v[208:211], v[228:231], v[90:105]
	v_mfma_f32_32x32x16_bf16 v[106:121], v[212:215], v[224:227], v[106:121]
	v_mfma_f32_32x32x16_bf16 v[122:137], v[212:215], v[228:231], v[122:137]
	s_waitcnt lgkmcnt(4)
	v_mfma_f32_32x32x16_bf16 v[34:49], v[232:235], v[240:243], v[34:49]
	s_waitcnt lgkmcnt(3)
	v_mfma_f32_32x32x16_bf16 v[50:65], v[232:235], v[244:247], v[50:65]
	s_waitcnt lgkmcnt(2)
	v_mfma_f32_32x32x16_bf16 v[2:17], v[236:239], v[240:243], v[2:17]
	v_mfma_f32_32x32x16_bf16 v[18:33], v[236:239], v[244:247], v[18:33]
	s_waitcnt lgkmcnt(1)
	v_mfma_f32_32x32x16_bf16 v[74:89], v[232:235], v[248:251], v[74:89]
	s_waitcnt lgkmcnt(0)
	v_mfma_f32_32x32x16_bf16 v[90:105], v[232:235], v[156:159], v[90:105]
	v_mfma_f32_32x32x16_bf16 v[106:121], v[236:239], v[248:251], v[106:121]
	v_mfma_f32_32x32x16_bf16 v[122:137], v[236:239], v[156:159], v[122:137]
	s_setprio 0
	s_sub_u32 s46, s46, 1
	s_cmp_lg_u32 s46, 0
	s_cbranch_scc1 .Lffn1_kloop
	s_waitcnt vmcnt(6)
	s_barrier
	s_setprio 1
	ds_read_b128 v[208:211], v138 offset:0
	ds_read_b128 v[216:219], v140 offset:0
	ds_read_b128 v[220:223], v140 offset:2048
	ds_read_b128 v[212:215], v138 offset:2048
	ds_read_b128 v[224:227], v140 offset:8192
	ds_read_b128 v[228:231], v140 offset:10240
	ds_read_b128 v[232:235], v139 offset:0
	ds_read_b128 v[240:243], v141 offset:0
	ds_read_b128 v[244:247], v141 offset:2048
	ds_read_b128 v[236:239], v139 offset:2048
	ds_read_b128 v[248:251], v141 offset:8192
	ds_read_b128 v[156:159], v141 offset:10240
	s_waitcnt lgkmcnt(10)
	v_mfma_f32_32x32x16_bf16 v[34:49], v[208:211], v[216:219], v[34:49]
	s_waitcnt lgkmcnt(9)
	v_mfma_f32_32x32x16_bf16 v[50:65], v[208:211], v[220:223], v[50:65]
	s_waitcnt lgkmcnt(8)
	v_mfma_f32_32x32x16_bf16 v[2:17], v[212:215], v[216:219], v[2:17]
	v_mfma_f32_32x32x16_bf16 v[18:33], v[212:215], v[220:223], v[18:33]
	s_waitcnt lgkmcnt(7)
	v_mfma_f32_32x32x16_bf16 v[74:89], v[208:211], v[224:227], v[74:89]
	s_waitcnt lgkmcnt(6)
	v_mfma_f32_32x32x16_bf16 v[90:105], v[208:211], v[228:231], v[90:105]
	v_mfma_f32_32x32x16_bf16 v[106:121], v[212:215], v[224:227], v[106:121]
	v_mfma_f32_32x32x16_bf16 v[122:137], v[212:215], v[228:231], v[122:137]
	s_waitcnt lgkmcnt(4)
	v_mfma_f32_32x32x16_bf16 v[34:49], v[232:235], v[240:243], v[34:49]
	s_waitcnt lgkmcnt(3)
	v_mfma_f32_32x32x16_bf16 v[50:65], v[232:235], v[244:247], v[50:65]
	s_waitcnt lgkmcnt(2)
	v_mfma_f32_32x32x16_bf16 v[2:17], v[236:239], v[240:243], v[2:17]
	v_mfma_f32_32x32x16_bf16 v[18:33], v[236:239], v[244:247], v[18:33]
	s_waitcnt lgkmcnt(1)
	v_mfma_f32_32x32x16_bf16 v[74:89], v[232:235], v[248:251], v[74:89]
	s_waitcnt lgkmcnt(0)
	v_mfma_f32_32x32x16_bf16 v[90:105], v[232:235], v[156:159], v[90:105]
	v_mfma_f32_32x32x16_bf16 v[106:121], v[236:239], v[248:251], v[106:121]
	v_mfma_f32_32x32x16_bf16 v[122:137], v[236:239], v[156:159], v[122:137]
	s_setprio 0
	s_waitcnt vmcnt(0)
	s_barrier
	s_setprio 1
	ds_read_b128 v[208:211], v138 offset:24576
	ds_read_b128 v[216:219], v140 offset:24576
	ds_read_b128 v[220:223], v140 offset:26624
	ds_read_b128 v[212:215], v138 offset:26624
	ds_read_b128 v[224:227], v140 offset:32768
	ds_read_b128 v[228:231], v140 offset:34816
	ds_read_b128 v[232:235], v139 offset:24576
	ds_read_b128 v[240:243], v141 offset:24576
	ds_read_b128 v[244:247], v141 offset:26624
	ds_read_b128 v[236:239], v139 offset:26624
	ds_read_b128 v[248:251], v141 offset:32768
	ds_read_b128 v[156:159], v141 offset:34816
	s_waitcnt lgkmcnt(10)
	v_mfma_f32_32x32x16_bf16 v[34:49], v[208:211], v[216:219], v[34:49]
	s_waitcnt lgkmcnt(9)
	v_mfma_f32_32x32x16_bf16 v[50:65], v[208:211], v[220:223], v[50:65]
	s_waitcnt lgkmcnt(8)
	v_mfma_f32_32x32x16_bf16 v[2:17], v[212:215], v[216:219], v[2:17]
	v_mfma_f32_32x32x16_bf16 v[18:33], v[212:215], v[220:223], v[18:33]
	s_waitcnt lgkmcnt(7)
	v_mfma_f32_32x32x16_bf16 v[74:89], v[208:211], v[224:227], v[74:89]
	s_waitcnt lgkmcnt(6)
	v_mfma_f32_32x32x16_bf16 v[90:105], v[208:211], v[228:231], v[90:105]
	v_mfma_f32_32x32x16_bf16 v[106:121], v[212:215], v[224:227], v[106:121]
	v_mfma_f32_32x32x16_bf16 v[122:137], v[212:215], v[228:231], v[122:137]
	s_waitcnt lgkmcnt(4)
	v_mfma_f32_32x32x16_bf16 v[34:49], v[232:235], v[240:243], v[34:49]
	s_waitcnt lgkmcnt(3)
	v_mfma_f32_32x32x16_bf16 v[50:65], v[232:235], v[244:247], v[50:65]
	s_waitcnt lgkmcnt(2)
	v_mfma_f32_32x32x16_bf16 v[2:17], v[236:239], v[240:243], v[2:17]
	v_mfma_f32_32x32x16_bf16 v[18:33], v[236:239], v[244:247], v[18:33]
	s_waitcnt lgkmcnt(1)
	v_mfma_f32_32x32x16_bf16 v[74:89], v[232:235], v[248:251], v[74:89]
	s_waitcnt lgkmcnt(0)
	v_mfma_f32_32x32x16_bf16 v[90:105], v[232:235], v[156:159], v[90:105]
	v_mfma_f32_32x32x16_bf16 v[106:121], v[236:239], v[248:251], v[106:121]
	v_mfma_f32_32x32x16_bf16 v[122:137], v[236:239], v[156:159], v[122:137]
	s_setprio 0
	s_barrier

; DI int BID() { int b = (int)__builtin_amdgcn_workgroup_id_x(); asm volatile("" : "+s"(b)); return b; }
; DI void run_phase(const Params& p, int ph, int l, int c, char* smem) {
;     ...
;     case PH_INPROJ: {
;       PF pf; int t = BID();
;       if (t < MTN * 46) { const u16* A0; const u16* W0; inproj_ptrs(p, l, t, A0, W0); gemm_issue(pf, A0, 1024, W0, 1024); }
;       for (; t < MTN * 46; t += gridDim.x) { const int tn = t + (int)gridDim.x; tile_inproj(p, l, ck, t, tn < MTN * 46 ? tn : -1, pf, smem); }
.LBB1_378:
	s_andn2_b64 vcc, exec, s[20:21]
	s_cbranch_vccnz .LBB1_428
	v_readlane_b32 s0, v255, 30
	s_cmp_gt_i32 s0, 1
	s_mov_b64 s[20:21], -1
	s_cbranch_scc0 .LBB1_410
	s_mov_b32 s16, s92
	s_bfe_u32 s0, s16, 0x10008
	s_bfe_u32 s20, s16, 0x20006
	s_and_b32 s16, s16, 63
	s_lshl_b32 s0, s0, 6
	s_lshl_b32 s20, s20, 8
	s_or_b32 s16, s16, s0
	s_or_b32 s16, s16, s20
	s_mov_b32 s14, 0
	s_cmpk_gt_i32 s16, 0x16ff
	s_cbranch_scc1 .LBB1_409
	s_ashr_i32 s0, s16, 7
	s_cmp_lt_i32 s0, 45
	s_cselect_b32 s20, s0, 0x45
	s_add_u32 s17, s18, 0x1c14c000
	s_addc_u32 s42, s19, 0
	s_lshl_b32 s0, s16, 18
	s_lshl_b32 s43, s16, 17
	s_and_b32 s0, s0, 0x1fc0000
	s_add_u32 s22, s17, s0
	v_readlane_b32 s24, v255, 28
	s_addc_u32 s23, s42, 0
	s_mul_i32 s21, s24, 0x1180000
	s_mul_hi_i32 s0, s24, 0x1180000
	s_add_u32 s52, s18, s21
	s_addc_u32 s53, s19, s0
	s_ashr_i32 s21, s20, 31
	s_lshl_b64 s[20:21], s[20:21], 18
	s_add_u32 s20, s52, s20
	s_addc_u32 s21, s53, s21
	s_lshl_b32 s26, s24, 7
	s_add_i32 s54, s2, -1
	s_ashr_i32 s27, s26, 31
	s_add_u32 s20, s18, 0x1e14c000
	s_addc_u32 s21, s19, 0
	s_add_u32 s22, s18, 0x10f80000
	s_addc_u32 s23, s19, 0
	v_readlane_b32 s25, v255, 29
	s_add_u32 s24, s18, 0xcb80000
	s_addc_u32 s25, s19, 0
	s_lshl_b64 s[26:27], s[26:27], 2
	s_add_u32 s0, s18, s26
	s_addc_u32 s27, s19, s27
	s_add_u32 s26, s0, 0x1c14a600
	s_addc_u32 s27, s27, 0
	s_add_u32 s55, s18, 0x1c144000
	s_addc_u32 s74, s19, 0
	s_lshl_b32 s75, s16, 7
	s_branch .LBB1_384

; DI RowSS rowss_load(const float* ps, int m0) { const int tid = TID(); const float* q = ps + (size_t)(m0 + (tid >> 1)) * 16 + (tid & 1) * 8; RowSS r; r.a = *(const f32x4*)q; r.b = *(const f32x4*)(q + 4); return r; }
; DI void zero_acc(f32x16 (&acc)[2][2]) {
; #pragma unroll
;   for (int a = 0; a < 2; ++a)
; #pragma unroll
;     for (int b = 0; b < 2; ++b)
; #pragma unroll
;       for (int r = 0; r < 16; ++r) acc[a][b][r] = 0.f;
; }
; DI void tile_inproj(const Params& p, int l, const Chunk& ck, int tile, int next, PF& pf, char* smem) {
;   float* Cs = (float*)smem; float* rinv_s = (float*)(smem + SMEM_CS);
;   const int mi = tile & (MTN - 1), nj = tile >> MTS; const int ni = (nj < 45) ? nj : 69; const int m0 = mi * 128;
;   const u16* Ap; const u16* Wt; inproj_ptrs(p, l, tile, Ap, Wt);
;   f32x16 acc[2][2]; zero_acc(acc);
;   const RowSS rss = rowss_load((const float*)(p.ws + OFF_PSIN), m0);
;   gemm_run<16>(pf, Ap, 1024, Wt, acc, smem);
;   if (next >= 0) { const u16* An; const u16* Wn; inproj_ptrs(p, l, next, An, Wn); gemm_issue(pf, An, 1024, Wn, 1024); }
.LBB1_383:
	s_add_i32 s43, s43, s59
	s_add_i32 s75, s75, s95
	s_xor_b32 s14, s14, 1
	s_cmp_eq_u32 s14, 1
	s_cbranch_scc0 .Linp_nextpair
	s_sub_i32 s16, s16, 0x180
	s_branch .LBB1_384
.Linp_nextpair:
	s_add_i32 s16, s16, 0x180
	s_cmpk_lt_i32 s16, 0x1700
	s_cbranch_scc0 .LBB1_409
.LBB1_384:
	s_mov_b32 s0, s16
	s_add_i32 s16, s16, s78
	s_cmpk_gt_i32 s16, 0x16ff
	s_cselect_b64 s[28:29], -1, 0
	s_cmpk_lt_i32 s16, 0x1700
	s_cselect_b32 s34, s16, -1
	s_ashr_i32 s0, s0, 7
	s_cmp_lt_i32 s0, 45
	s_cselect_b64 s[36:37], -1, 0
	s_and_b64 s[30:31], s[36:37], exec
	v_mov_b32_e32 v0, v172
	s_cselect_b32 s30, s0, 0x45
	s_and_b32 s79, s75, 0x3f80
	s_and_b32 s0, s43, 0xfe0000
	s_waitcnt lgkmcnt(0)
	v_ashrrev_i32_e32 v2, 1, v0
	v_add_u32_e32 v2, s79, v2
	v_ashrrev_i32_e32 v3, 31, v2
	v_lshlrev_b64 v[2:3], 6, v[2:3]
	v_lshlrev_b32_e32 v0, 5, v0
	v_lshl_add_u64 v[2:3], s[20:21], 0, v[2:3]
	v_and_b32_e32 v0, 32, v0
	v_lshl_add_u64 v[2:3], v[2:3], 0, v[0:1]
	global_load_dwordx4 v[130:133], v[2:3], off offset:16
	global_load_dwordx4 v[134:137], v[2:3], off
	s_lshl_b32 s0, s0, 1
	s_add_u32 s40, s17, s0
	s_addc_u32 s41, s42, 0
	s_ashr_i32 s31, s30, 31
	s_lshl_b64 s[56:57], s[30:31], 18
	s_add_u32 vcc_lo, s52, s56
	s_addc_u32 vcc_hi, s53, s57
	s_setprio 0
	s_waitcnt lgkmcnt(0)
	s_cmp_lg_u32 s14, 0
	s_cbranch_scc1 .Linp_pass1
	s_mov_b64 s[48:49], s[40:41]
	s_lshl_b32 s15, s30, 13
	s_add_u32 s50, s52, s15
	s_addc_u32 s51, s53, 0
	s_mov_b32 s13, 0x5a000
	v_and_b32_e32 v144, 63, v172
	v_lshrrev_b32_e32 v145, 6, v172
	v_lshrrev_b32_e32 v146, 4, v144
	v_xor_b32_e32 v146, v146, v144
	v_and_b32_e32 v146, 3, v146
	v_lshlrev_b32_e32 v146, 4, v146
	v_lshrrev_b32_e32 v147, 2, v144
	v_lshl_add_u32 v138, v145, 5, v147
	v_lshl_add_u32 v138, v138, 11, v146
	v_add_u32_e32 v139, 0x7c00, v138
	v_lshl_add_u32 v140, v145, 6, v147
	v_lshl_add_u32 v140, v140, 6, v146
	v_mov_b32_e32 v141, v140
	v_mov_b32_e32 v142, v140
	v_mov_b32_e32 v143, v140
	v_readfirstlane_b32 s46, v145
	s_lshl_b32 s47, s46, 12
	s_lshl_b32 s46, s46, 11
	s_add_u32 s47, s47, 0x2000
	v_and_b32_e32 v146, 31, v144
	v_lshrrev_b32_e32 v147, 5, v144
	v_lshrrev_b32_e32 v144, 2, v146
	v_and_b32_e32 v144, 3, v144
	v_xor_b32_e32 v144, v144, v147
	v_lshlrev_b32_e32 v144, 4, v144
	v_lshl_add_u32 v144, v146, 6, v144
	v_lshrrev_b32_e32 v146, 1, v145
	v_and_b32_e32 v147, 1, v145
	v_lshl_add_u32 v126, v146, 12, v144
	v_lshl_add_u32 v128, v147, 12, v144
	v_add_u32_e32 v128, 0x2000, v128
	v_xor_b32_e32 v127, 32, v126
	v_xor_b32_e32 v129, 32, v128
	s_cmp_eq_u32 s30, 44
	s_cselect_b32 s15, 1, 0
	s_cmp_ge_u32 s46, 0x1000
	s_cselect_b32 s15, s15, 0
	s_cmp_lg_u32 s15, 0
	s_cbranch_scc0 .Linp_nokr
	s_add_u32 s50, s52, 0x113e000
	s_addc_u32 s51, s53, 0
	s_mov_b32 s13, 0x2000
.Linp_nokr:
	s_barrier
	v_mov_b32_e32 v34, 0
	v_mov_b32_e32 v35, 0
	v_mov_b32_e32 v36, 0
	v_mov_b32_e32 v37, 0
	v_mov_b32_e32 v38, 0
	v_mov_b32_e32 v39, 0
	v_mov_b32_e32 v40, 0
	v_mov_b32_e32 v41, 0
	v_mov_b32_e32 v42, 0
	v_mov_b32_e32 v43, 0
	v_mov_b32_e32 v44, 0
	v_mov_b32_e32 v45, 0
	v_mov_b32_e32 v46, 0
	v_mov_b32_e32 v47, 0
	v_mov_b32_e32 v48, 0
	v_mov_b32_e32 v49, 0
	v_mov_b32_e32 v50, 0
	v_mov_b32_e32 v51, 0
	v_mov_b32_e32 v52, 0
	v_mov_b32_e32 v53, 0
	v_mov_b32_e32 v54, 0
	v_mov_b32_e32 v55, 0
	v_mov_b32_e32 v56, 0
	v_mov_b32_e32 v57, 0
	v_mov_b32_e32 v58, 0
	v_mov_b32_e32 v59, 0
	v_mov_b32_e32 v60, 0
	v_mov_b32_e32 v61, 0
	v_mov_b32_e32 v62, 0
	v_mov_b32_e32 v63, 0
	v_mov_b32_e32 v64, 0
	v_mov_b32_e32 v65, 0
	v_mov_b32_e32 v2, 0
	v_mov_b32_e32 v3, 0
	v_mov_b32_e32 v4, 0
	v_mov_b32_e32 v5, 0
	v_mov_b32_e32 v6, 0
	v_mov_b32_e32 v7, 0
	v_mov_b32_e32 v8, 0
	v_mov_b32_e32 v9, 0
	v_mov_b32_e32 v10, 0
	v_mov_b32_e32 v11, 0
	v_mov_b32_e32 v12, 0
	v_mov_b32_e32 v13, 0
	v_mov_b32_e32 v14, 0
	v_mov_b32_e32 v15, 0
	v_mov_b32_e32 v16, 0
	v_mov_b32_e32 v17, 0
	v_mov_b32_e32 v18, 0
	v_mov_b32_e32 v19, 0
	v_mov_b32_e32 v20, 0
	v_mov_b32_e32 v21, 0
	v_mov_b32_e32 v22, 0
	v_mov_b32_e32 v23, 0
	v_mov_b32_e32 v24, 0
	v_mov_b32_e32 v25, 0
	v_mov_b32_e32 v26, 0
	v_mov_b32_e32 v27, 0
	v_mov_b32_e32 v28, 0
	v_mov_b32_e32 v29, 0
	v_mov_b32_e32 v30, 0
	v_mov_b32_e32 v31, 0
	v_mov_b32_e32 v32, 0
	v_mov_b32_e32 v33, 0
	v_mov_b32_e32 v74, 0
	v_mov_b32_e32 v75, 0
	v_mov_b32_e32 v76, 0
	v_mov_b32_e32 v77, 0
	v_mov_b32_e32 v78, 0
	v_mov_b32_e32 v79, 0
	v_mov_b32_e32 v80, 0
	v_mov_b32_e32 v81, 0
	v_mov_b32_e32 v82, 0
	v_mov_b32_e32 v83, 0
	v_mov_b32_e32 v84, 0
	v_mov_b32_e32 v85, 0
	v_mov_b32_e32 v86, 0
	v_mov_b32_e32 v87, 0
	v_mov_b32_e32 v88, 0
	v_mov_b32_e32 v89, 0
	v_mov_b32_e32 v90, 0
	v_mov_b32_e32 v91, 0
	v_mov_b32_e32 v92, 0
	v_mov_b32_e32 v93, 0
	v_mov_b32_e32 v94, 0
	v_mov_b32_e32 v95, 0
	v_mov_b32_e32 v96, 0
	v_mov_b32_e32 v97, 0
	v_mov_b32_e32 v98, 0
	v_mov_b32_e32 v99, 0
	v_mov_b32_e32 v100, 0
	v_mov_b32_e32 v101, 0
	v_mov_b32_e32 v102, 0
	v_mov_b32_e32 v103, 0
	v_mov_b32_e32 v104, 0
	v_mov_b32_e32 v105, 0
	v_mov_b32_e32 v106, 0
	v_mov_b32_e32 v107, 0
	v_mov_b32_e32 v108, 0
	v_mov_b32_e32 v109, 0
	v_mov_b32_e32 v110, 0
	v_mov_b32_e32 v111, 0
	v_mov_b32_e32 v112, 0
	v_mov_b32_e32 v113, 0
	v_mov_b32_e32 v114, 0
	v_mov_b32_e32 v115, 0
	v_mov_b32_e32 v116, 0
	v_mov_b32_e32 v117, 0
	v_mov_b32_e32 v118, 0
	v_mov_b32_e32 v119, 0
	v_mov_b32_e32 v120, 0
	v_mov_b32_e32 v121, 0
	v_mov_b32_e32 v208, 0
	v_mov_b32_e32 v209, 0
	v_mov_b32_e32 v210, 0
	v_mov_b32_e32 v211, 0
	v_mov_b32_e32 v212, 0
	v_mov_b32_e32 v213, 0
	v_mov_b32_e32 v214, 0
	v_mov_b32_e32 v215, 0
	v_mov_b32_e32 v216, 0
	v_mov_b32_e32 v217, 0
	v_mov_b32_e32 v218, 0
	v_mov_b32_e32 v219, 0
	v_mov_b32_e32 v220, 0
	v_mov_b32_e32 v221, 0
	v_mov_b32_e32 v222, 0
	v_mov_b32_e32 v223, 0
	s_add_u32 m0, s46, 0x0
	s_nop 0
	global_load_lds_dwordx4 v138, s[48:49]
	global_load_lds_dwordx4 v139, s[48:49] offset:1024
	s_add_u32 m0, s47, 0x0
	s_nop 0
	global_load_lds_dwordx4 v140, s[50:51]
	global_load_lds_dwordx4 v141, s[50:51] offset:1024
	global_load_lds_dwordx4 v142, s[50:51] offset:2048
	global_load_lds_dwordx4 v143, s[50:51] offset:3072
	s_add_u32 m0, s46, 0x6000
	s_add_u32 s48, s48, 0x40
	s_addc_u32 s49, s49, 0
	global_load_lds_dwordx4 v138, s[48:49]
	global_load_lds_dwordx4 v139, s[48:49] offset:1024
	s_add_u32 m0, s47, 0x6000
	s_add_u32 s50, s50, s13
	s_addc_u32 s51, s51, 0
	global_load_lds_dwordx4 v140, s[50:51]
	global_load_lds_dwordx4 v141, s[50:51] offset:1024
	global_load_lds_dwordx4 v142, s[50:51] offset:2048
	global_load_lds_dwordx4 v143, s[50:51] offset:3072
	s_mov_b32 s12, 10
; #define BLOAD(A_, B_, kt) do { _Pragma("unroll") for (int i = 0; i < 4; ++i) { \
;     A_[i] = *(const u32x4*)((const char*)Ap + (aoff + (unsigned)(32 * i * lda + (kt) * 64) * 2u)); B_[i] = *(const u32x4*)((const char*)Wt + (woff + (unsigned)(32 * i * K + (kt) * 64) * 2u)); } } while (0)
; #define BLOAD(A_, B_, kt) do { _Pragma("unroll") for (int i = 0; i < 4; ++i) { \
;     A_[i] = *(const u32x4*)((const char*)Ap + (aoff + (unsigned)(32 * i * lda + (kt) * 64) * 2u)); B_[i] = *(const u32x4*)((const char*)Wt + (woff + (unsigned)(32 * i * K + (kt) * 64) * 2u)); } } while (0)
; #define BSTORE(A_, B_, buf) do { _Pragma("unroll") for (int i = 0; i < 4; ++i) { \
;     *(u32x4*)&As[(buf) * GBUF + (srow + 32 * i) * LDT + sc8] = A_[i]; \
;     *(u32x4*)&Bs[(buf) * GBUF + (srow + 32 * i) * LDT + sc8] = B_[i]; } } while (0)
; template <int NK>
; DI void gemm_run(PF& pf, const u16* __restrict__ Ap, int lda, const u16* __restrict__ Wt, f32x16 (&acc)[2][2], char* smem) {
;     ...
;   __builtin_amdgcn_s_setprio(0);
;   __syncthreads();
;   BSTORE(pf.a0, pf.b0, 0);
;   BLOAD(pf.a0, pf.b0, 2);
;   __syncthreads();
; #pragma unroll
;   for (int kt = 0; kt < nk; kt += 2) {
;     BCOMP(0);
;     BSTORE(pf.a1, pf.b1, 1);
;     if (kt + 3 < nk) BLOAD(pf.a1, pf.b1, kt + 3);
;     __syncthreads();
;     BCOMP(1);
;     if (kt + 2 < nk) { BSTORE(pf.a0, pf.b0, 0); if (kt + 4 < nk) BLOAD(pf.a0, pf.b0, kt + 4); }
;     __syncthreads();
.Linp_kloop:
	s_waitcnt vmcnt(6)
	s_barrier
	s_setprio 1
	ds_read_b128 v[224:227], v126 offset:0
	ds_read_b128 v[232:235], v128 offset:0
	ds_read_b128 v[236:239], v128 offset:2048
	ds_read_b128 v[228:231], v126 offset:2048
	ds_read_b128 v[240:243], v128 offset:8192
	ds_read_b128 v[244:247], v128 offset:10240
	ds_read_b128 v[248:251], v127 offset:0
	ds_read_b128 v[160:163], v129 offset:0
	ds_read_b128 v[164:167], v129 offset:2048
	ds_read_b128 v[156:159], v127 offset:2048
	ds_read_b128 v[168:171], v129 offset:8192
	ds_read_b128 v[122:125], v129 offset:10240
	s_add_u32 m0, s46, 0xc000
	s_add_u32 s48, s48, 0x40
	s_addc_u32 s49, s49, 0
	global_load_lds_dwordx4 v138, s[48:49]
	global_load_lds_dwordx4 v139, s[48:49] offset:1024
	s_add_u32 m0, s47, 0xc000
	s_add_u32 s50, s50, s13
	s_addc_u32 s51, s51, 0
	global_load_lds_dwordx4 v140, s[50:51]
	global_load_lds_dwordx4 v141, s[50:51] offset:1024
	global_load_lds_dwordx4 v142, s[50:51] offset:2048
	global_load_lds_dwordx4 v143, s[50:51] offset:3072
	s_waitcnt lgkmcnt(10)
	v_mfma_f32_32x32x16_bf16 v[34:49], v[224:227], v[232:235], v[34:49]
	s_waitcnt lgkmcnt(9)
	v_mfma_f32_32x32x16_bf16 v[50:65], v[224:227], v[236:239], v[50:65]
	s_waitcnt lgkmcnt(8)
	v_mfma_f32_32x32x16_bf16 v[2:17], v[228:231], v[232:235], v[2:17]
	v_mfma_f32_32x32x16_bf16 v[18:33], v[228:231], v[236:239], v[18:33]
	s_waitcnt lgkmcnt(7)
	v_mfma_f32_32x32x16_bf16 v[74:89], v[224:227], v[240:243], v[74:89]
	s_waitcnt lgkmcnt(6)
	v_mfma_f32_32x32x16_bf16 v[90:105], v[224:227], v[244:247], v[90:105]
	v_mfma_f32_32x32x16_bf16 v[106:121], v[228:231], v[240:243], v[106:121]
	v_mfma_f32_32x32x16_bf16 v[208:223], v[228:231], v[244:247], v[208:223]
	s_waitcnt lgkmcnt(4)
	v_mfma_f32_32x32x16_bf16 v[34:49], v[248:251], v[160:163], v[34:49]
	s_waitcnt lgkmcnt(3)
	v_mfma_f32_32x32x16_bf16 v[50:65], v[248:251], v[164:167], v[50:65]
	s_waitcnt lgkmcnt(2)
	v_mfma_f32_32x32x16_bf16 v[2:17], v[156:159], v[160:163], v[2:17]
	v_mfma_f32_32x32x16_bf16 v[18:33], v[156:159], v[164:167], v[18:33]
	s_waitcnt lgkmcnt(1)
	v_mfma_f32_32x32x16_bf16 v[74:89], v[248:251], v[168:171], v[74:89]
	s_waitcnt lgkmcnt(0)
	v_mfma_f32_32x32x16_bf16 v[90:105], v[248:251], v[122:125], v[90:105]
	v_mfma_f32_32x32x16_bf16 v[106:121], v[156:159], v[168:171], v[106:121]
	v_mfma_f32_32x32x16_bf16 v[208:223], v[156:159], v[122:125], v[208:223]
	s_setprio 0
	s_waitcnt vmcnt(6)
	s_barrier
	s_setprio 1
	ds_read_b128 v[224:227], v126 offset:24576
	ds_read_b128 v[232:235], v128 offset:24576
	ds_read_b128 v[236:239], v128 offset:26624
	ds_read_b128 v[228:231], v126 offset:26624
	ds_read_b128 v[240:243], v128 offset:32768
	ds_read_b128 v[244:247], v128 offset:34816
	ds_read_b128 v[248:251], v127 offset:24576
	ds_read_b128 v[160:163], v129 offset:24576
	ds_read_b128 v[164:167], v129 offset:26624
	ds_read_b128 v[156:159], v127 offset:26624
	ds_read_b128 v[168:171], v129 offset:32768
	ds_read_b128 v[122:125], v129 offset:34816
	s_add_u32 m0, s46, 0x0
	s_add_u32 s48, s48, 0x40
	s_addc_u32 s49, s49, 0
	global_load_lds_dwordx4 v138, s[48:49]
	global_load_lds_dwordx4 v139, s[48:49] offset:1024
	s_add_u32 m0, s47, 0x0
	s_add_u32 s50, s50, s13
	s_addc_u32 s51, s51, 0
	global_load_lds_dwordx4 v140, s[50:51]
	global_load_lds_dwordx4 v141, s[50:51] offset:1024
	global_load_lds_dwordx4 v142, s[50:51] offset:2048
	global_load_lds_dwordx4 v143, s[50:51] offset:3072
	s_waitcnt lgkmcnt(10)
	v_mfma_f32_32x32x16_bf16 v[34:49], v[224:227], v[232:235], v[34:49]
	s_waitcnt lgkmcnt(9)
	v_mfma_f32_32x32x16_bf16 v[50:65], v[224:227], v[236:239], v[50:65]
	s_waitcnt lgkmcnt(8)
	v_mfma_f32_32x32x16_bf16 v[2:17], v[228:231], v[232:235], v[2:17]
	v_mfma_f32_32x32x16_bf16 v[18:33], v[228:231], v[236:239], v[18:33]
	s_waitcnt lgkmcnt(7)
	v_mfma_f32_32x32x16_bf16 v[74:89], v[224:227], v[240:243], v[74:89]
	s_waitcnt lgkmcnt(6)
	v_mfma_f32_32x32x16_bf16 v[90:105], v[224:227], v[244:247], v[90:105]
	v_mfma_f32_32x32x16_bf16 v[106:121], v[228:231], v[240:243], v[106:121]
	v_mfma_f32_32x32x16_bf16 v[208:223], v[228:231], v[244:247], v[208:223]
	s_waitcnt lgkmcnt(4)
	v_mfma_f32_32x32x16_bf16 v[34:49], v[248:251], v[160:163], v[34:49]
	s_waitcnt lgkmcnt(3)
	v_mfma_f32_32x32x16_bf16 v[50:65], v[248:251], v[164:167], v[50:65]
	s_waitcnt lgkmcnt(2)
	v_mfma_f32_32x32x16_bf16 v[2:17], v[156:159], v[160:163], v[2:17]
	v_mfma_f32_32x32x16_bf16 v[18:33], v[156:159], v[164:167], v[18:33]
	s_waitcnt lgkmcnt(1)
	v_mfma_f32_32x32x16_bf16 v[74:89], v[248:251], v[168:171], v[74:89]
	s_waitcnt lgkmcnt(0)
	v_mfma_f32_32x32x16_bf16 v[90:105], v[248:251], v[122:125], v[90:105]
	v_mfma_f32_32x32x16_bf16 v[106:121], v[156:159], v[168:171], v[106:121]
	v_mfma_f32_32x32x16_bf16 v[208:223], v[156:159], v[122:125], v[208:223]
	s_setprio 0
	s_waitcnt vmcnt(6)
	s_barrier
; #define BLOAD(A_, B_, kt) do { _Pragma("unroll") for (int i = 0; i < 4; ++i) { \
;     A_[i] = *(const u32x4*)((const char*)Ap + (aoff + (unsigned)(32 * i * lda + (kt) * 64) * 2u)); B_[i] = *(const u32x4*)((const char*)Wt + (woff + (unsigned)(32 * i * K + (kt) * 64) * 2u)); } } while (0)
; #define BLOAD(A_, B_, kt) do { _Pragma("unroll") for (int i = 0; i < 4; ++i) { \
;     A_[i] = *(const u32x4*)((const char*)Ap + (aoff + (unsigned)(32 * i * lda + (kt) * 64) * 2u)); B_[i] = *(const u32x4*)((const char*)Wt + (woff + (unsigned)(32 * i * K + (kt) * 64) * 2u)); } } while (0)
; #define BSTORE(A_, B_, buf) do { _Pragma("unroll") for (int i = 0; i < 4; ++i) { \
;     *(u32x4*)&As[(buf) * GBUF + (srow + 32 * i) * LDT + sc8] = A_[i]; \
;     *(u32x4*)&Bs[(buf) * GBUF + (srow + 32 * i) * LDT + sc8] = B_[i]; } } while (0)
; template <int NK>
; DI void gemm_run(PF& pf, const u16* __restrict__ Ap, int lda, const u16* __restrict__ Wt, f32x16 (&acc)[2][2], char* smem) {
;     ...
;   __builtin_amdgcn_s_setprio(0);
;   __syncthreads();
;   BSTORE(pf.a0, pf.b0, 0);
;   BLOAD(pf.a0, pf.b0, 2);
;   __syncthreads();
; #pragma unroll
;   for (int kt = 0; kt < nk; kt += 2) {
;     BCOMP(0);
;     BSTORE(pf.a1, pf.b1, 1);
;     if (kt + 3 < nk) BLOAD(pf.a1, pf.b1, kt + 3);
;     __syncthreads();
;     BCOMP(1);
;     if (kt + 2 < nk) { BSTORE(pf.a0, pf.b0, 0); if (kt + 4 < nk) BLOAD(pf.a0, pf.b0, kt + 4); }
;     __syncthreads();
	s_setprio 1
	ds_read_b128 v[224:227], v126 offset:49152
	ds_read_b128 v[232:235], v128 offset:49152
	ds_read_b128 v[236:239], v128 offset:51200
	ds_read_b128 v[228:231], v126 offset:51200
	ds_read_b128 v[240:243], v128 offset:57344
	ds_read_b128 v[244:247], v128 offset:59392
	ds_read_b128 v[248:251], v127 offset:49152
	ds_read_b128 v[160:163], v129 offset:49152
	ds_read_b128 v[164:167], v129 offset:51200
	ds_read_b128 v[156:159], v127 offset:51200
	ds_read_b128 v[168:171], v129 offset:57344
	ds_read_b128 v[122:125], v129 offset:59392
	s_add_u32 m0, s46, 0x6000
	s_add_u32 s48, s48, 0x40
	s_addc_u32 s49, s49, 0
	global_load_lds_dwordx4 v138, s[48:49]
	global_load_lds_dwordx4 v139, s[48:49] offset:1024
	s_add_u32 m0, s47, 0x6000
	s_add_u32 s50, s50, s13
	s_addc_u32 s51, s51, 0
	global_load_lds_dwordx4 v140, s[50:51]
	global_load_lds_dwordx4 v141, s[50:51] offset:1024
	global_load_lds_dwordx4 v142, s[50:51] offset:2048
	global_load_lds_dwordx4 v143, s[50:51] offset:3072
	s_waitcnt lgkmcnt(10)
	v_mfma_f32_32x32x16_bf16 v[34:49], v[224:227], v[232:235], v[34:49]
	s_waitcnt lgkmcnt(9)
	v_mfma_f32_32x32x16_bf16 v[50:65], v[224:227], v[236:239], v[50:65]
	s_waitcnt lgkmcnt(8)
	v_mfma_f32_32x32x16_bf16 v[2:17], v[228:231], v[232:235], v[2:17]
	v_mfma_f32_32x32x16_bf16 v[18:33], v[228:231], v[236:239], v[18:33]
	s_waitcnt lgkmcnt(7)
	v_mfma_f32_32x32x16_bf16 v[74:89], v[224:227], v[240:243], v[74:89]
	s_waitcnt lgkmcnt(6)
	v_mfma_f32_32x32x16_bf16 v[90:105], v[224:227], v[244:247], v[90:105]
	v_mfma_f32_32x32x16_bf16 v[106:121], v[228:231], v[240:243], v[106:121]
	v_mfma_f32_32x32x16_bf16 v[208:223], v[228:231], v[244:247], v[208:223]
	s_waitcnt lgkmcnt(4)
	v_mfma_f32_32x32x16_bf16 v[34:49], v[248:251], v[160:163], v[34:49]
	s_waitcnt lgkmcnt(3)
	v_mfma_f32_32x32x16_bf16 v[50:65], v[248:251], v[164:167], v[50:65]
	s_waitcnt lgkmcnt(2)
	v_mfma_f32_32x32x16_bf16 v[2:17], v[156:159], v[160:163], v[2:17]
	v_mfma_f32_32x32x16_bf16 v[18:33], v[156:159], v[164:167], v[18:33]
	s_waitcnt lgkmcnt(1)
	v_mfma_f32_32x32x16_bf16 v[74:89], v[248:251], v[168:171], v[74:89]
	s_waitcnt lgkmcnt(0)
	v_mfma_f32_32x32x16_bf16 v[90:105], v[248:251], v[122:125], v[90:105]
	v_mfma_f32_32x32x16_bf16 v[106:121], v[156:159], v[168:171], v[106:121]
	v_mfma_f32_32x32x16_bf16 v[208:223], v[156:159], v[122:125], v[208:223]
	s_setprio 0
	s_sub_u32 s12, s12, 1
	s_cmp_lg_u32 s12, 0
	s_cbranch_scc1 .Linp_kloop
	s_waitcnt vmcnt(6)
	s_barrier
	s_setprio 1
	ds_read_b128 v[224:227], v126 offset:0
	ds_read_b128 v[232:235], v128 offset:0
	ds_read_b128 v[236:239], v128 offset:2048
	ds_read_b128 v[228:231], v126 offset:2048
	ds_read_b128 v[240:243], v128 offset:8192
	ds_read_b128 v[244:247], v128 offset:10240
	ds_read_b128 v[248:251], v127 offset:0
	ds_read_b128 v[160:163], v129 offset:0
	ds_read_b128 v[164:167], v129 offset:2048
	ds_read_b128 v[156:159], v127 offset:2048
	ds_read_b128 v[168:171], v129 offset:8192
	ds_read_b128 v[122:125], v129 offset:10240
	s_waitcnt lgkmcnt(10)
	v_mfma_f32_32x32x16_bf16 v[34:49], v[224:227], v[232:235], v[34:49]
	s_waitcnt lgkmcnt(9)
	v_mfma_f32_32x32x16_bf16 v[50:65], v[224:227], v[236:239], v[50:65]
	s_waitcnt lgkmcnt(8)
	v_mfma_f32_32x32x16_bf16 v[2:17], v[228:231], v[232:235], v[2:17]
	v_mfma_f32_32x32x16_bf16 v[18:33], v[228:231], v[236:239], v[18:33]
	s_waitcnt lgkmcnt(7)
	v_mfma_f32_32x32x16_bf16 v[74:89], v[224:227], v[240:243], v[74:89]
	s_waitcnt lgkmcnt(6)
	v_mfma_f32_32x32x16_bf16 v[90:105], v[224:227], v[244:247], v[90:105]
	v_mfma_f32_32x32x16_bf16 v[106:121], v[228:231], v[240:243], v[106:121]
	v_mfma_f32_32x32x16_bf16 v[208:223], v[228:231], v[244:247], v[208:223]
	s_waitcnt lgkmcnt(4)
	v_mfma_f32_32x32x16_bf16 v[34:49], v[248:251], v[160:163], v[34:49]
	s_waitcnt lgkmcnt(3)
	v_mfma_f32_32x32x16_bf16 v[50:65], v[248:251], v[164:167], v[50:65]
	s_waitcnt lgkmcnt(2)
	v_mfma_f32_32x32x16_bf16 v[2:17], v[156:159], v[160:163], v[2:17]
	v_mfma_f32_32x32x16_bf16 v[18:33], v[156:159], v[164:167], v[18:33]
	s_waitcnt lgkmcnt(1)
	v_mfma_f32_32x32x16_bf16 v[74:89], v[248:251], v[168:171], v[74:89]
	s_waitcnt lgkmcnt(0)
	v_mfma_f32_32x32x16_bf16 v[90:105], v[248:251], v[122:125], v[90:105]
	v_mfma_f32_32x32x16_bf16 v[106:121], v[156:159], v[168:171], v[106:121]
	v_mfma_f32_32x32x16_bf16 v[208:223], v[156:159], v[122:125], v[208:223]
	s_setprio 0
	s_waitcnt vmcnt(0)
	s_barrier
	s_setprio 1
	ds_read_b128 v[224:227], v126 offset:24576
	ds_read_b128 v[232:235], v128 offset:24576
	ds_read_b128 v[236:239], v128 offset:26624
	ds_read_b128 v[228:231], v126 offset:26624
	ds_read_b128 v[240:243], v128 offset:32768
	ds_read_b128 v[244:247], v128 offset:34816
	ds_read_b128 v[248:251], v127 offset:24576
	ds_read_b128 v[160:163], v129 offset:24576
	ds_read_b128 v[164:167], v129 offset:26624
	ds_read_b128 v[156:159], v127 offset:26624
	ds_read_b128 v[168:171], v129 offset:32768
	ds_read_b128 v[122:125], v129 offset:34816
	s_waitcnt lgkmcnt(10)
	v_mfma_f32_32x32x16_bf16 v[34:49], v[224:227], v[232:235], v[34:49]
	s_waitcnt lgkmcnt(9)
	v_mfma_f32_32x32x16_bf16 v[50:65], v[224:227], v[236:239], v[50:65]
	s_waitcnt lgkmcnt(8)
	v_mfma_f32_32x32x16_bf16 v[2:17], v[228:231], v[232:235], v[2:17]
	v_mfma_f32_32x32x16_bf16 v[18:33], v[228:231], v[236:239], v[18:33]
	s_waitcnt lgkmcnt(7)
	v_mfma_f32_32x32x16_bf16 v[74:89], v[224:227], v[240:243], v[74:89]
	s_waitcnt lgkmcnt(6)
	v_mfma_f32_32x32x16_bf16 v[90:105], v[224:227], v[244:247], v[90:105]
	v_mfma_f32_32x32x16_bf16 v[106:121], v[228:231], v[240:243], v[106:121]
	v_mfma_f32_32x32x16_bf16 v[208:223], v[228:231], v[244:247], v[208:223]
	s_waitcnt lgkmcnt(4)
	v_mfma_f32_32x32x16_bf16 v[34:49], v[248:251], v[160:163], v[34:49]
	s_waitcnt lgkmcnt(3)
	v_mfma_f32_32x32x16_bf16 v[50:65], v[248:251], v[164:167], v[50:65]
	s_waitcnt lgkmcnt(2)
	v_mfma_f32_32x32x16_bf16 v[2:17], v[156:159], v[160:163], v[2:17]
	v_mfma_f32_32x32x16_bf16 v[18:33], v[156:159], v[164:167], v[18:33]
	s_waitcnt lgkmcnt(1)
	v_mfma_f32_32x32x16_bf16 v[74:89], v[248:251], v[168:171], v[74:89]
	s_waitcnt lgkmcnt(0)
	v_mfma_f32_32x32x16_bf16 v[90:105], v[248:251], v[122:125], v[90:105]
	v_mfma_f32_32x32x16_bf16 v[106:121], v[156:159], v[168:171], v[106:121]
	v_mfma_f32_32x32x16_bf16 v[208:223], v[156:159], v[122:125], v[208:223]
	s_setprio 0
	s_barrier
	s_branch .Linp_post
; DI int TID() { int t = (int)__builtin_amdgcn_workitem_id_x(); asm volatile("" : "+v"(t)); return t; }
; DI RowSS rowss_load(const float* ps, int m0) { const int tid = TID(); const float* q = ps + (size_t)(m0 + (tid >> 1)) * 16 + (tid & 1) * 8; RowSS r; r.a = *(const f32x4*)q; r.b = *(const f32x4*)(q + 4); return r; }
; DI void rowss_finish(const RowSS& r, float* rinv_s) {
;   const int tid = TID();
;   float s = (r.a[0] + r.a[1]) + (r.a[2] + r.a[3]) + (r.b[0] + r.b[1]) + (r.b[2] + r.b[3]);
;   s += __shfl_xor(s, 1);
;   if ((tid & 1) == 0) rinv_s[tid >> 1] = rsqrtf(s * (1.f / 1024.f) + EPS);
; }
; DI void tile_inproj(const Params& p, int l, const Chunk& ck, int tile, int next, PF& pf, char* smem) {
;   float* Cs = (float*)smem; float* rinv_s = (float*)(smem + SMEM_CS);
;   const int mi = tile & (MTN - 1), nj = tile >> MTS; const int ni = (nj < 45) ? nj : 69; const int m0 = mi * 128;
;   const u16* Ap; const u16* Wt; inproj_ptrs(p, l, tile, Ap, Wt);
;   f32x16 acc[2][2]; zero_acc(acc);
;   const RowSS rss = rowss_load((const float*)(p.ws + OFF_PSIN), m0);
;   gemm_run<16>(pf, Ap, 1024, Wt, acc, smem);
;   if (next >= 0) { const u16* An; const u16* Wn; inproj_ptrs(p, l, next, An, Wn); gemm_issue(pf, An, 1024, Wn, 1024); }
;   rowss_finish(rss, rinv_s);
;   acc_to_cs(acc, Cs);
.Linp_pass1:
	v_mov_b32_e32 v34, v74
	v_mov_b32_e32 v35, v75
	v_mov_b32_e32 v36, v76
	v_mov_b32_e32 v37, v77
	v_mov_b32_e32 v38, v78
	v_mov_b32_e32 v39, v79
	v_mov_b32_e32 v40, v80
	v_mov_b32_e32 v41, v81
	v_mov_b32_e32 v42, v82
	v_mov_b32_e32 v43, v83
	v_mov_b32_e32 v44, v84
	v_mov_b32_e32 v45, v85
	v_mov_b32_e32 v46, v86
	v_mov_b32_e32 v47, v87
	v_mov_b32_e32 v48, v88
	v_mov_b32_e32 v49, v89
	v_mov_b32_e32 v50, v90
	v_mov_b32_e32 v51, v91
	v_mov_b32_e32 v52, v92
	v_mov_b32_e32 v53, v93
	v_mov_b32_e32 v54, v94
	v_mov_b32_e32 v55, v95
	v_mov_b32_e32 v56, v96
	v_mov_b32_e32 v57, v97
	v_mov_b32_e32 v58, v98
	v_mov_b32_e32 v59, v99
	v_mov_b32_e32 v60, v100
	v_mov_b32_e32 v61, v101
	v_mov_b32_e32 v62, v102
	v_mov_b32_e32 v63, v103
	v_mov_b32_e32 v64, v104
	v_mov_b32_e32 v65, v105
	v_mov_b32_e32 v2, v106
	v_mov_b32_e32 v3, v107
	v_mov_b32_e32 v4, v108
	v_mov_b32_e32 v5, v109
	v_mov_b32_e32 v6, v110
	v_mov_b32_e32 v7, v111
	v_mov_b32_e32 v8, v112
	v_mov_b32_e32 v9, v113
	v_mov_b32_e32 v10, v114
	v_mov_b32_e32 v11, v115
	v_mov_b32_e32 v12, v116
	v_mov_b32_e32 v13, v117
	v_mov_b32_e32 v14, v118
	v_mov_b32_e32 v15, v119
	v_mov_b32_e32 v16, v120
	v_mov_b32_e32 v17, v121
	v_mov_b32_e32 v18, v208
	v_mov_b32_e32 v19, v209
	v_mov_b32_e32 v20, v210
	v_mov_b32_e32 v21, v211
	v_mov_b32_e32 v22, v212
	v_mov_b32_e32 v23, v213
	v_mov_b32_e32 v24, v214
	v_mov_b32_e32 v25, v215
	v_mov_b32_e32 v26, v216
	v_mov_b32_e32 v27, v217
	v_mov_b32_e32 v28, v218
	v_mov_b32_e32 v29, v219
	v_mov_b32_e32 v30, v220
	v_mov_b32_e32 v31, v221
	v_mov_b32_e32 v32, v222
	v_mov_b32_e32 v33, v223
	s_waitcnt vmcnt(0)
	s_barrier
.Linp_post:
.LBB1_386:
	v_add_f32_e32 v0, v134, v135
	v_add_f32_e32 v134, v136, v137
	v_add_f32_e32 v0, v0, v134
	v_add_f32_e32 v130, v130, v131
	v_add_f32_e32 v0, v0, v130
	v_add_f32_e32 v130, v132, v133
	v_cmp_lt_i32_e32 vcc, v200, v194
	v_add_f32_e32 v131, v130, v0
	s_nop 0
	v_cndmask_b32_e32 v0, v193, v200, vcc
	v_lshlrev_b32_e32 v130, 2, v0
	ds_bpermute_b32 v132, v130, v131
	v_mov_b32_e32 v0, v172
	s_nop 0
	v_and_b32_e32 v133, 1, v0
	v_cmp_eq_u32_e32 vcc, 0, v133
	s_and_saveexec_b64 s[34:35], vcc
	s_cbranch_execz .LBB1_388
	s_waitcnt lgkmcnt(0)
	v_add_f32_e32 v131, v131, v132
	v_fmamk_f32 v131, v131, 0x3a800000, v188
	v_mul_f32_e32 v132, 0x4b800000, v131
	v_cmp_gt_f32_e32 vcc, s39, v131
	v_lshl_add_u32 v0, v0, 1, v201
	s_nop 0
	v_cndmask_b32_e32 v131, v131, v132, vcc
	v_rsq_f32_e32 v131, v131
	s_nop 0
	v_mul_f32_e32 v132, 0x45800000, v131
	v_cndmask_b32_e32 v131, v131, v132, vcc
	ds_write_b32 v0, v131
